# ssd_out unit: k-loop loads hoisted and both token halves issue their 16 y/z loads together (all load ladders of the unit removed)
# baseline (speedup 1.0000x reference)
.LBB0_1290:
	s_or_b64 exec, exec, s[4:5]
	v_readlane_b32 s2, v254, 53
	s_waitcnt lgkmcnt(0)
	s_barrier
	v_mov_b32_e32 v0, s2
	ds_read_b32 v0, v0
	s_mov_b64 s[4:5], -1
	s_waitcnt lgkmcnt(0)
	v_readfirstlane_b32 s2, v0
	s_cmpk_gt_i32 s2, 0xff
	s_cbranch_scc1 .LBB0_1285
	s_ashr_i32 s4, s2, 5
	s_and_b32 s3, s2, 31
	s_ashr_i32 s5, s4, 31
	s_lshl_b32 s2, s2, 2
	s_lshl_b32 s16, s3, 6
	s_lshl_b64 s[14:15], s[4:5], 7
	s_and_b32 s2, s2, 0x78
	s_add_u32 s3, s14, s88
	s_addc_u32 s14, s15, 0
	s_add_u32 s2, s3, s2
	s_addc_u32 s3, s14, 0
	s_lshl_b64 s[2:3], s[2:3], 14
	v_lshl_add_u64 v[4:5], v[86:87], 0, s[2:3]
	v_mov_b32_e32 v103, v96
	v_mov_b32_e32 v105, v96
	s_lshl_b64 s[4:5], s[4:5], 11
	v_lshl_add_u64 v[80:81], v[4:5], 0, v[102:103]
	v_lshl_add_u64 v[82:83], v[4:5], 0, v[104:105]
	s_or_b32 s4, s4, s16
	global_load_dwordx4 v[0:3], v[80:81], off
	global_load_dwordx4 v[4:7], v[82:83], off
	s_lshl_b64 s[14:15], s[4:5], 9
	v_lshl_add_u64 v[12:13], v[88:89], 0, s[14:15]
	v_mov_b32_e32 v107, v96
	v_mov_b32_e32 v109, v96
	v_lshl_add_u64 v[110:111], v[12:13], 0, v[106:107]
	v_lshl_add_u64 v[112:113], v[12:13], 0, v[108:109]
	global_load_dwordx4 v[8:11], v[110:111], off
	global_load_dwordx4 v[12:15], v[112:113], off
	global_load_dwordx4 v[64:67], v[80:81], off offset:32
	global_load_dwordx4 v[68:71], v[82:83], off offset:32
	global_load_dwordx4 v[72:75], v[110:111], off offset:32
	global_load_dwordx4 v[76:79], v[112:113], off offset:32
	global_load_dwordx4 v[116:119], v[80:81], off offset:64
	global_load_dwordx4 v[120:123], v[82:83], off offset:64
	global_load_dwordx4 v[132:135], v[110:111], off offset:64
	global_load_dwordx4 v[136:139], v[112:113], off offset:64
	global_load_dwordx4 v[140:143], v[80:81], off offset:96
	global_load_dwordx4 v[148:151], v[82:83], off offset:96
	global_load_dwordx4 v[152:155], v[110:111], off offset:96
	global_load_dwordx4 v[158:161], v[112:113], off offset:96
	global_load_dwordx4 v[162:165], v[80:81], off offset:128
	global_load_dwordx4 v[166:169], v[82:83], off offset:128
	global_load_dwordx4 v[170:173], v[110:111], off offset:128
	global_load_dwordx4 v[186:189], v[112:113], off offset:128
	global_load_dwordx4 v[190:193], v[80:81], off offset:160
	global_load_dwordx4 v[194:197], v[82:83], off offset:160
	global_load_dwordx4 v[198:201], v[110:111], off offset:160
	global_load_dwordx4 v[202:205], v[112:113], off offset:160
	global_load_dwordx4 v[206:209], v[80:81], off offset:192
	global_load_dwordx4 v[210:213], v[82:83], off offset:192
	global_load_dwordx4 v[214:217], v[110:111], off offset:192
	global_load_dwordx4 v[218:221], v[112:113], off offset:192
	global_load_dwordx4 v[222:225], v[80:81], off offset:224
	global_load_dwordx4 v[226:229], v[82:83], off offset:224
	global_load_dwordx4 v[230:233], v[110:111], off offset:224
	global_load_dwordx4 v[236:239], v[112:113], off offset:224
	s_waitcnt vmcnt(29)
	v_mfma_f32_32x32x16_bf16 v[48:63], v[0:3], v[8:11], 0
	v_mfma_f32_32x32x16_bf16 v[32:47], v[4:7], v[8:11], 0
	s_waitcnt vmcnt(28)
	v_mfma_f32_32x32x16_bf16 v[16:31], v[0:3], v[12:15], 0
	v_mfma_f32_32x32x16_bf16 v[0:15], v[4:7], v[12:15], 0
	s_waitcnt vmcnt(25)
	v_mfma_f32_32x32x16_bf16 v[48:63], v[64:67], v[72:75], v[48:63]
	v_mfma_f32_32x32x16_bf16 v[32:47], v[68:71], v[72:75], v[32:47]
	s_waitcnt vmcnt(24)
	v_mfma_f32_32x32x16_bf16 v[16:31], v[64:67], v[76:79], v[16:31]
	v_mfma_f32_32x32x16_bf16 v[0:15], v[68:71], v[76:79], v[0:15]
	s_waitcnt vmcnt(21)
	v_mfma_f32_32x32x16_bf16 v[48:63], v[116:119], v[132:135], v[48:63]
	v_mfma_f32_32x32x16_bf16 v[32:47], v[120:123], v[132:135], v[32:47]
	s_waitcnt vmcnt(20)
	v_mfma_f32_32x32x16_bf16 v[16:31], v[116:119], v[136:139], v[16:31]
	v_mfma_f32_32x32x16_bf16 v[0:15], v[120:123], v[136:139], v[0:15]
	s_waitcnt vmcnt(17)
	v_mfma_f32_32x32x16_bf16 v[48:63], v[140:143], v[152:155], v[48:63]
	v_mfma_f32_32x32x16_bf16 v[32:47], v[148:151], v[152:155], v[32:47]
	s_waitcnt vmcnt(16)
	v_mfma_f32_32x32x16_bf16 v[16:31], v[140:143], v[158:161], v[16:31]
	v_mfma_f32_32x32x16_bf16 v[0:15], v[148:151], v[158:161], v[0:15]
	s_waitcnt vmcnt(13)
	v_mfma_f32_32x32x16_bf16 v[48:63], v[162:165], v[170:173], v[48:63]
	v_mfma_f32_32x32x16_bf16 v[32:47], v[166:169], v[170:173], v[32:47]
	s_waitcnt vmcnt(12)
	v_mfma_f32_32x32x16_bf16 v[16:31], v[162:165], v[186:189], v[16:31]
	v_mfma_f32_32x32x16_bf16 v[0:15], v[166:169], v[186:189], v[0:15]
	s_waitcnt vmcnt(9)
	v_mfma_f32_32x32x16_bf16 v[48:63], v[190:193], v[198:201], v[48:63]
	v_mfma_f32_32x32x16_bf16 v[32:47], v[194:197], v[198:201], v[32:47]
	s_waitcnt vmcnt(8)
	v_mfma_f32_32x32x16_bf16 v[16:31], v[190:193], v[202:205], v[16:31]
	v_mfma_f32_32x32x16_bf16 v[0:15], v[194:197], v[202:205], v[0:15]
	s_waitcnt vmcnt(5)
	v_mfma_f32_32x32x16_bf16 v[48:63], v[206:209], v[214:217], v[48:63]
	v_mfma_f32_32x32x16_bf16 v[32:47], v[210:213], v[214:217], v[32:47]
	s_waitcnt vmcnt(4)
	v_mfma_f32_32x32x16_bf16 v[16:31], v[206:209], v[218:221], v[16:31]
	v_mfma_f32_32x32x16_bf16 v[0:15], v[210:213], v[218:221], v[0:15]
	s_barrier
	s_waitcnt vmcnt(1)
	v_mfma_f32_32x32x16_bf16 v[32:47], v[226:229], v[230:233], v[32:47]
	s_waitcnt vmcnt(0)
	v_mfma_f32_32x32x16_bf16 v[0:15], v[226:229], v[236:239], v[0:15]
	v_mov_b32_e32 v69, s5
	v_or_b32_e32 v68, s4, v84
	v_lshlrev_b64 v[110:111], 11, v[68:69]
	v_mad_u64_u32 v[130:131], s[2:3], v68, s42, v[98:99]
	v_lshl_add_u64 v[128:129], v[94:95], 0, v[110:111]
	v_mfma_f32_32x32x16_bf16 v[48:63], v[222:225], v[230:233], v[48:63]
	v_mfma_f32_32x32x16_bf16 v[16:31], v[222:225], v[236:239], v[16:31]
	v_lshlrev_b64 v[64:65], 5, v[68:69]
	v_lshl_add_u64 v[64:65], s[8:9], 0, v[64:65]
	global_load_dword v142, v[64:65], off
	v_mov_b32_e32 v68, 0x2800
	v_mad_i32_i24 v131, s5, v68, v131
	global_load_dwordx4 v[64:67], v[128:129], off
	global_load_dwordx4 v[112:115], v[130:131], off
	global_load_dwordx4 v[120:123], v[128:129], off offset:32
	global_load_dwordx4 v[132:135], v[130:131], off offset:32
	global_load_dwordx4 v[80:83], v[128:129], off offset:64
	global_load_dwordx4 v[76:79], v[130:131], off offset:64
	global_load_dwordx4 v[72:75], v[128:129], off offset:96
	global_load_dwordx4 v[68:71], v[130:131], off offset:96
	global_load_dwordx4 v[186:189], v[128:129], off offset:128
	global_load_dwordx4 v[190:193], v[130:131], off offset:128
	global_load_dwordx4 v[194:197], v[128:129], off offset:160
	global_load_dwordx4 v[198:201], v[130:131], off offset:160
	global_load_dwordx4 v[202:205], v[128:129], off offset:192
	global_load_dwordx4 v[206:209], v[130:131], off offset:192
	global_load_dwordx4 v[210:213], v[128:129], off offset:224
	global_load_dwordx4 v[214:217], v[130:131], off offset:224
	s_waitcnt vmcnt(16)
	v_exp_f32_e32 v124, v142
	s_waitcnt vmcnt(14)
	v_mul_f32_e32 v103, 0xbfb8aa3b, v112
	v_fma_f32 v105, v112, s43, -v103
	v_rndne_f32_e32 v107, v103
	v_fmac_f32_e32 v105, 0xb2a5705f, v112
	v_sub_f32_e32 v103, v103, v107
	v_add_f32_e32 v103, v103, v105
	v_exp_f32_e32 v103, v103
	v_cvt_i32_f32_e32 v105, v107
	v_cmp_nlt_f32_e32 vcc, s34, v112
	v_pk_fma_f32 v[48:49], v[48:49], v[124:125], v[64:65] op_sel_hi:[1,0,1]
	v_pk_fma_f32 v[50:51], v[50:51], v[124:125], v[66:67] op_sel_hi:[1,0,1]
	v_ldexp_f32 v103, v103, v105
	v_cndmask_b32_e32 v103, 0, v103, vcc
	v_cmp_ngt_f32_e32 vcc, s35, v112
	s_waitcnt vmcnt(13)
	v_pk_fma_f32 v[52:53], v[52:53], v[124:125], v[120:121] op_sel_hi:[1,0,1]
	v_cndmask_b32_e32 v116, v179, v103, vcc
	v_mul_f32_e32 v103, 0xbfb8aa3b, v113
	v_fma_f32 v105, v113, s43, -v103
	v_rndne_f32_e32 v107, v103
	v_fmac_f32_e32 v105, 0xb2a5705f, v113
	v_sub_f32_e32 v103, v103, v107
	v_add_f32_e32 v103, v103, v105
	v_exp_f32_e32 v103, v103
	v_cvt_i32_f32_e32 v105, v107
	v_cmp_nlt_f32_e32 vcc, s34, v113
	v_ldexp_f32 v103, v103, v105
	s_nop 0
	v_cndmask_b32_e32 v103, 0, v103, vcc
	v_cmp_ngt_f32_e32 vcc, s35, v113
	s_nop 1
	v_cndmask_b32_e32 v117, v179, v103, vcc
	v_pk_add_f32 v[64:65], v[116:117], 1.0 op_sel_hi:[1,0]
	s_nop 0
	v_div_scale_f32 v103, s[2:3], v65, v65, v113
	v_rcp_f32_e32 v105, v103
	s_nop 0
	v_fma_f32 v107, -v103, v105, 1.0
	v_fmac_f32_e32 v105, v107, v105
	v_div_scale_f32 v107, vcc, v113, v65, v113
	v_mul_f32_e32 v109, v107, v105
	v_fma_f32 v116, -v103, v109, v107
	v_fmac_f32_e32 v109, v116, v105
	v_fma_f32 v103, -v103, v109, v107
	v_div_fmas_f32 v103, v103, v105, v109
	v_div_fixup_f32 v65, v103, v65, v113
	v_div_scale_f32 v103, s[2:3], v64, v64, v112
	v_rcp_f32_e32 v105, v103
	s_nop 0
	v_fma_f32 v107, -v103, v105, 1.0
	v_fmac_f32_e32 v105, v107, v105
	v_div_scale_f32 v107, vcc, v112, v64, v112
	v_mul_f32_e32 v109, v107, v105
	v_fma_f32 v113, -v103, v109, v107
	v_fmac_f32_e32 v109, v113, v105
	v_fma_f32 v103, -v103, v109, v107
	v_div_fmas_f32 v103, v103, v105, v109
	v_div_fixup_f32 v64, v103, v64, v112
	v_pk_mul_f32 v[116:117], v[48:49], v[64:65]
	v_mul_f32_e32 v64, 0xbfb8aa3b, v114
	v_fma_f32 v65, v114, s43, -v64
	v_rndne_f32_e32 v103, v64
	v_fmac_f32_e32 v65, 0xb2a5705f, v114
	v_sub_f32_e32 v64, v64, v103
	v_add_f32_e32 v64, v64, v65
	v_exp_f32_e32 v64, v64
	v_cvt_i32_f32_e32 v65, v103
	v_cmp_nlt_f32_e32 vcc, s34, v114
	v_mul_f32_e32 v48, v117, v117
	v_pk_fma_f32 v[48:49], v[116:117], v[116:117], v[48:49] op_sel_hi:[1,1,0]
	v_ldexp_f32 v64, v64, v65
	v_mul_f32_e32 v65, 0xbfb8aa3b, v115
	v_fma_f32 v103, v115, s43, -v65
	v_rndne_f32_e32 v105, v65
	v_fmac_f32_e32 v103, 0xb2a5705f, v115
	v_sub_f32_e32 v65, v65, v105
	v_add_f32_e32 v65, v65, v103
	v_exp_f32_e32 v65, v65
	v_cvt_i32_f32_e32 v103, v105
	v_cndmask_b32_e32 v64, 0, v64, vcc
	v_cmp_ngt_f32_e32 vcc, s35, v114
	v_ldexp_f32 v65, v65, v103
	s_nop 0
	v_cndmask_b32_e32 v64, v179, v64, vcc
	v_cmp_nlt_f32_e32 vcc, s34, v115
	s_nop 1
	v_cndmask_b32_e32 v65, 0, v65, vcc
	v_cmp_ngt_f32_e32 vcc, s35, v115
	s_nop 1
	v_cndmask_b32_e32 v65, v179, v65, vcc
	v_pk_add_f32 v[64:65], v[64:65], 1.0 op_sel_hi:[1,0]
	s_nop 0
	v_div_scale_f32 v66, s[2:3], v65, v65, v115
	v_rcp_f32_e32 v67, v66
	s_nop 0
	v_fma_f32 v103, -v66, v67, 1.0
	v_fmac_f32_e32 v67, v103, v67
	v_div_scale_f32 v103, vcc, v115, v65, v115
	v_mul_f32_e32 v105, v103, v67
	v_fma_f32 v107, -v66, v105, v103
	v_fmac_f32_e32 v105, v107, v67
	v_fma_f32 v66, -v66, v105, v103
	v_div_fmas_f32 v66, v66, v67, v105
	v_div_fixup_f32 v65, v66, v65, v115
	v_div_scale_f32 v66, s[2:3], v64, v64, v114
	v_rcp_f32_e32 v67, v66
	s_nop 0
	v_fma_f32 v103, -v66, v67, 1.0
	v_fmac_f32_e32 v67, v103, v67
	v_div_scale_f32 v103, vcc, v114, v64, v114
	v_mul_f32_e32 v105, v103, v67
	v_fma_f32 v107, -v66, v105, v103
	v_fmac_f32_e32 v105, v107, v67
	v_fma_f32 v66, -v66, v105, v103
	v_div_fmas_f32 v66, v66, v67, v105
	v_div_fixup_f32 v64, v66, v64, v114
	v_pk_mul_f32 v[118:119], v[50:51], v[64:65]
	s_waitcnt vmcnt(12)
	v_cmp_nlt_f32_e32 vcc, s34, v132
	v_pk_fma_f32 v[48:49], v[118:119], v[118:119], v[48:49]
	v_mul_f32_e32 v50, v119, v119
	v_pk_add_f32 v[48:49], v[50:51], v[48:49] op_sel_hi:[0,1]
	v_mul_f32_e32 v50, 0xbfb8aa3b, v132
	v_fma_f32 v51, v132, s43, -v50
	v_rndne_f32_e32 v64, v50
	v_fmac_f32_e32 v51, 0xb2a5705f, v132
	v_sub_f32_e32 v50, v50, v64
	v_add_f32_e32 v50, v50, v51
	v_exp_f32_e32 v50, v50
	v_cvt_i32_f32_e32 v51, v64
	v_ldexp_f32 v50, v50, v51
	v_mul_f32_e32 v51, 0xbfb8aa3b, v133
	v_fma_f32 v64, v133, s43, -v51
	v_rndne_f32_e32 v65, v51
	v_fmac_f32_e32 v64, 0xb2a5705f, v133
	v_sub_f32_e32 v51, v51, v65
	v_add_f32_e32 v51, v51, v64
	v_exp_f32_e32 v51, v51
	v_cvt_i32_f32_e32 v64, v65
	v_cndmask_b32_e32 v50, 0, v50, vcc
	v_cmp_ngt_f32_e32 vcc, s35, v132
	v_ldexp_f32 v51, v51, v64
	s_nop 0
	v_cndmask_b32_e32 v50, v179, v50, vcc
	v_cmp_nlt_f32_e32 vcc, s34, v133
	s_nop 1
	v_cndmask_b32_e32 v51, 0, v51, vcc
	v_cmp_ngt_f32_e32 vcc, s35, v133
	s_nop 1
	v_cndmask_b32_e32 v51, v179, v51, vcc
	v_pk_add_f32 v[50:51], v[50:51], 1.0 op_sel_hi:[1,0]
	s_nop 0
	v_div_scale_f32 v64, s[2:3], v51, v51, v133
	v_rcp_f32_e32 v65, v64
	s_nop 0
	v_fma_f32 v66, -v64, v65, 1.0
	v_fmac_f32_e32 v65, v66, v65
	v_div_scale_f32 v66, vcc, v133, v51, v133
	v_mul_f32_e32 v67, v66, v65
	v_fma_f32 v103, -v64, v67, v66
	v_fmac_f32_e32 v67, v103, v65
	v_fma_f32 v64, -v64, v67, v66
	v_div_fmas_f32 v64, v64, v65, v67
	v_div_fixup_f32 v51, v64, v51, v133
	v_div_scale_f32 v64, s[2:3], v50, v50, v132
	v_rcp_f32_e32 v65, v64
	s_nop 0
	v_fma_f32 v66, -v64, v65, 1.0
	v_fmac_f32_e32 v65, v66, v65
	v_div_scale_f32 v66, vcc, v132, v50, v132
	v_mul_f32_e32 v67, v66, v65
	v_fma_f32 v103, -v64, v67, v66
	v_fmac_f32_e32 v67, v103, v65
	v_fma_f32 v64, -v64, v67, v66
	v_div_fmas_f32 v64, v64, v65, v67
	v_div_fixup_f32 v50, v64, v50, v132
	v_pk_mul_f32 v[112:113], v[52:53], v[50:51]
	v_cmp_nlt_f32_e32 vcc, s34, v134
	v_pk_fma_f32 v[48:49], v[112:113], v[112:113], v[48:49]
	v_mul_f32_e32 v50, v113, v113
	v_pk_add_f32 v[48:49], v[50:51], v[48:49] op_sel_hi:[0,1]
	v_mul_f32_e32 v50, 0xbfb8aa3b, v134
	v_fma_f32 v51, v134, s43, -v50
	v_rndne_f32_e32 v52, v50
	v_fmac_f32_e32 v51, 0xb2a5705f, v134
	v_sub_f32_e32 v50, v50, v52
	v_add_f32_e32 v50, v50, v51
	v_exp_f32_e32 v50, v50
	v_cvt_i32_f32_e32 v51, v52
	v_ldexp_f32 v50, v50, v51
	v_mul_f32_e32 v51, 0xbfb8aa3b, v135
	v_fma_f32 v52, v135, s43, -v51
	v_rndne_f32_e32 v53, v51
	v_fmac_f32_e32 v52, 0xb2a5705f, v135
	v_sub_f32_e32 v51, v51, v53
	v_add_f32_e32 v51, v51, v52
	v_exp_f32_e32 v51, v51
	v_cvt_i32_f32_e32 v52, v53
	v_cndmask_b32_e32 v50, 0, v50, vcc
	v_cmp_ngt_f32_e32 vcc, s35, v134
	v_ldexp_f32 v51, v51, v52
	s_nop 0
	v_cndmask_b32_e32 v50, v179, v50, vcc
	v_cmp_nlt_f32_e32 vcc, s34, v135
	v_pk_fma_f32 v[52:53], v[54:55], v[124:125], v[122:123] op_sel_hi:[1,0,1]
	s_nop 0
	v_cndmask_b32_e32 v51, 0, v51, vcc
	v_cmp_ngt_f32_e32 vcc, s35, v135
	s_nop 1
	v_cndmask_b32_e32 v51, v179, v51, vcc
	v_pk_add_f32 v[50:51], v[50:51], 1.0 op_sel_hi:[1,0]
	s_nop 0
	v_div_scale_f32 v54, s[2:3], v51, v51, v135
	v_rcp_f32_e32 v55, v54
	s_nop 0
	v_fma_f32 v64, -v54, v55, 1.0
	v_fmac_f32_e32 v55, v64, v55
	v_div_scale_f32 v64, vcc, v135, v51, v135
	v_mul_f32_e32 v65, v64, v55
	v_fma_f32 v66, -v54, v65, v64
	v_fmac_f32_e32 v65, v66, v55
	v_fma_f32 v54, -v54, v65, v64
	v_div_fmas_f32 v54, v54, v55, v65
	v_div_fixup_f32 v51, v54, v51, v135
	v_div_scale_f32 v54, s[2:3], v50, v50, v134
	v_rcp_f32_e32 v55, v54
	s_nop 0
	v_fma_f32 v64, -v54, v55, 1.0
	v_fmac_f32_e32 v55, v64, v55
	v_div_scale_f32 v64, vcc, v134, v50, v134
	v_mul_f32_e32 v65, v64, v55
	v_fma_f32 v66, -v54, v65, v64
	v_fmac_f32_e32 v65, v66, v55
	v_fma_f32 v54, -v54, v65, v64
	v_div_fmas_f32 v54, v54, v55, v65
	v_div_fixup_f32 v50, v54, v50, v134
	v_pk_mul_f32 v[114:115], v[52:53], v[50:51]
	s_waitcnt vmcnt(10)
	v_cmp_nlt_f32_e32 vcc, s34, v76
	v_pk_fma_f32 v[48:49], v[114:115], v[114:115], v[48:49]
	v_mul_f32_e32 v50, v115, v115
	v_pk_add_f32 v[48:49], v[50:51], v[48:49] op_sel_hi:[0,1]
	v_mul_f32_e32 v50, 0xbfb8aa3b, v76
	v_fma_f32 v51, v76, s43, -v50
	v_rndne_f32_e32 v52, v50
	v_fmac_f32_e32 v51, 0xb2a5705f, v76
	v_sub_f32_e32 v50, v50, v52
	v_add_f32_e32 v50, v50, v51
	v_exp_f32_e32 v50, v50
	v_cvt_i32_f32_e32 v51, v52
	v_ldexp_f32 v50, v50, v51
	v_mul_f32_e32 v51, 0xbfb8aa3b, v77
	v_fma_f32 v52, v77, s43, -v51
	v_rndne_f32_e32 v53, v51
	v_fmac_f32_e32 v52, 0xb2a5705f, v77
	v_sub_f32_e32 v51, v51, v53
	v_add_f32_e32 v51, v51, v52
	v_exp_f32_e32 v51, v51
	v_cvt_i32_f32_e32 v52, v53
	v_cndmask_b32_e32 v50, 0, v50, vcc
	v_cmp_ngt_f32_e32 vcc, s35, v76
	v_ldexp_f32 v51, v51, v52
	s_nop 0
	v_cndmask_b32_e32 v50, v179, v50, vcc
	v_cmp_nlt_f32_e32 vcc, s34, v77
	v_pk_fma_f32 v[52:53], v[56:57], v[124:125], v[80:81] op_sel_hi:[1,0,1]
	s_nop 0
	v_cndmask_b32_e32 v51, 0, v51, vcc
	v_cmp_ngt_f32_e32 vcc, s35, v77
	s_nop 1
	v_cndmask_b32_e32 v51, v179, v51, vcc
	v_pk_add_f32 v[50:51], v[50:51], 1.0 op_sel_hi:[1,0]
	s_nop 0
	v_div_scale_f32 v54, s[2:3], v51, v51, v77
	v_rcp_f32_e32 v55, v54
	s_nop 0
	v_fma_f32 v56, -v54, v55, 1.0
	v_fmac_f32_e32 v55, v56, v55
	v_div_scale_f32 v56, vcc, v77, v51, v77
	v_mul_f32_e32 v57, v56, v55
	v_fma_f32 v64, -v54, v57, v56
	v_fmac_f32_e32 v57, v64, v55
	v_fma_f32 v54, -v54, v57, v56
	v_div_fmas_f32 v54, v54, v55, v57
	v_div_fixup_f32 v51, v54, v51, v77
	v_div_scale_f32 v54, s[2:3], v50, v50, v76
	v_rcp_f32_e32 v55, v54
	s_nop 0
	v_fma_f32 v56, -v54, v55, 1.0
	v_fmac_f32_e32 v55, v56, v55
	v_div_scale_f32 v56, vcc, v76, v50, v76
	v_mul_f32_e32 v57, v56, v55
	v_fma_f32 v64, -v54, v57, v56
	v_fmac_f32_e32 v57, v64, v55
	v_fma_f32 v54, -v54, v57, v56
	v_div_fmas_f32 v54, v54, v55, v57
	v_div_fixup_f32 v50, v54, v50, v76
	v_pk_mul_f32 v[80:81], v[52:53], v[50:51]
	v_cmp_nlt_f32_e32 vcc, s34, v78
	v_pk_fma_f32 v[48:49], v[80:81], v[80:81], v[48:49]
	v_mul_f32_e32 v50, v81, v81
	v_pk_add_f32 v[48:49], v[50:51], v[48:49] op_sel_hi:[0,1]
	v_mul_f32_e32 v50, 0xbfb8aa3b, v78
	v_fma_f32 v51, v78, s43, -v50
	v_rndne_f32_e32 v52, v50
	v_fmac_f32_e32 v51, 0xb2a5705f, v78
	v_sub_f32_e32 v50, v50, v52
	v_add_f32_e32 v50, v50, v51
	v_exp_f32_e32 v50, v50
	v_cvt_i32_f32_e32 v51, v52
	v_ldexp_f32 v50, v50, v51
	v_mul_f32_e32 v51, 0xbfb8aa3b, v79
	v_fma_f32 v52, v79, s43, -v51
	v_rndne_f32_e32 v53, v51
	v_fmac_f32_e32 v52, 0xb2a5705f, v79
	v_sub_f32_e32 v51, v51, v53
	v_add_f32_e32 v51, v51, v52
	v_exp_f32_e32 v51, v51
	v_cvt_i32_f32_e32 v52, v53
	v_cndmask_b32_e32 v50, 0, v50, vcc
	v_cmp_ngt_f32_e32 vcc, s35, v78
	v_ldexp_f32 v51, v51, v52
	s_nop 0
	v_cndmask_b32_e32 v50, v179, v50, vcc
	v_cmp_nlt_f32_e32 vcc, s34, v79
	v_pk_fma_f32 v[52:53], v[58:59], v[124:125], v[82:83] op_sel_hi:[1,0,1]
	s_nop 0
	v_cndmask_b32_e32 v51, 0, v51, vcc
	v_cmp_ngt_f32_e32 vcc, s35, v79
	s_nop 1
	v_cndmask_b32_e32 v51, v179, v51, vcc
	v_pk_add_f32 v[50:51], v[50:51], 1.0 op_sel_hi:[1,0]
	s_nop 0
	v_div_scale_f32 v54, s[2:3], v51, v51, v79
	v_rcp_f32_e32 v55, v54
	s_nop 0
	v_fma_f32 v56, -v54, v55, 1.0
	v_fmac_f32_e32 v55, v56, v55
	v_div_scale_f32 v56, vcc, v79, v51, v79
	v_mul_f32_e32 v57, v56, v55
	v_fma_f32 v58, -v54, v57, v56
	v_fmac_f32_e32 v57, v58, v55
	v_fma_f32 v54, -v54, v57, v56
	v_div_fmas_f32 v54, v54, v55, v57
	v_div_fixup_f32 v51, v54, v51, v79
	v_div_scale_f32 v54, s[2:3], v50, v50, v78
	v_rcp_f32_e32 v55, v54
	s_nop 0
	v_fma_f32 v56, -v54, v55, 1.0
	v_fmac_f32_e32 v55, v56, v55
	v_div_scale_f32 v56, vcc, v78, v50, v78
	v_mul_f32_e32 v57, v56, v55
	v_fma_f32 v58, -v54, v57, v56
	v_fmac_f32_e32 v57, v58, v55
	v_fma_f32 v54, -v54, v57, v56
	v_div_fmas_f32 v54, v54, v55, v57
	v_div_fixup_f32 v50, v54, v50, v78
	v_pk_mul_f32 v[82:83], v[52:53], v[50:51]
	s_waitcnt vmcnt(8)
	v_cmp_nlt_f32_e32 vcc, s34, v68
	v_pk_fma_f32 v[48:49], v[82:83], v[82:83], v[48:49]
	v_mul_f32_e32 v50, v83, v83
	v_pk_add_f32 v[48:49], v[50:51], v[48:49] op_sel_hi:[0,1]
	v_mul_f32_e32 v50, 0xbfb8aa3b, v68
	v_fma_f32 v51, v68, s43, -v50
	v_rndne_f32_e32 v52, v50
	v_fmac_f32_e32 v51, 0xb2a5705f, v68
	v_sub_f32_e32 v50, v50, v52
	v_add_f32_e32 v50, v50, v51
	v_exp_f32_e32 v50, v50
	v_cvt_i32_f32_e32 v51, v52
	v_ldexp_f32 v50, v50, v51
	v_mul_f32_e32 v51, 0xbfb8aa3b, v69
	v_fma_f32 v52, v69, s43, -v51
	v_rndne_f32_e32 v53, v51
	v_fmac_f32_e32 v52, 0xb2a5705f, v69
	v_sub_f32_e32 v51, v51, v53
	v_add_f32_e32 v51, v51, v52
	v_exp_f32_e32 v51, v51
	v_cvt_i32_f32_e32 v52, v53
	v_cndmask_b32_e32 v50, 0, v50, vcc
	v_cmp_ngt_f32_e32 vcc, s35, v68
	v_ldexp_f32 v51, v51, v52
	s_nop 0
	v_cndmask_b32_e32 v50, v179, v50, vcc
	v_cmp_nlt_f32_e32 vcc, s34, v69
	v_pk_fma_f32 v[52:53], v[60:61], v[124:125], v[72:73] op_sel_hi:[1,0,1]
	s_nop 0
	v_cndmask_b32_e32 v51, 0, v51, vcc
	v_cmp_ngt_f32_e32 vcc, s35, v69
	s_nop 1
	v_cndmask_b32_e32 v51, v179, v51, vcc
	v_pk_add_f32 v[50:51], v[50:51], 1.0 op_sel_hi:[1,0]
	s_nop 0
	v_div_scale_f32 v54, s[2:3], v51, v51, v69
	v_rcp_f32_e32 v55, v54
	s_nop 0
	v_fma_f32 v56, -v54, v55, 1.0
	v_fmac_f32_e32 v55, v56, v55
	v_div_scale_f32 v56, vcc, v69, v51, v69
	v_mul_f32_e32 v57, v56, v55
	v_fma_f32 v58, -v54, v57, v56
	v_fmac_f32_e32 v57, v58, v55
	v_fma_f32 v54, -v54, v57, v56
	v_div_fmas_f32 v54, v54, v55, v57
	v_div_fixup_f32 v51, v54, v51, v69
	v_div_scale_f32 v54, s[2:3], v50, v50, v68
	v_rcp_f32_e32 v55, v54
	s_nop 0
	v_fma_f32 v56, -v54, v55, 1.0
	v_fmac_f32_e32 v55, v56, v55
	v_div_scale_f32 v56, vcc, v68, v50, v68
	v_mul_f32_e32 v57, v56, v55
	v_fma_f32 v58, -v54, v57, v56
	v_fmac_f32_e32 v57, v58, v55
	v_fma_f32 v54, -v54, v57, v56
	v_div_fmas_f32 v54, v54, v55, v57
	v_div_fixup_f32 v50, v54, v50, v68
	v_pk_mul_f32 v[120:121], v[52:53], v[50:51]
	v_cmp_nlt_f32_e32 vcc, s34, v70
	v_pk_fma_f32 v[48:49], v[120:121], v[120:121], v[48:49]
	v_mul_f32_e32 v50, v121, v121
	v_pk_add_f32 v[48:49], v[50:51], v[48:49] op_sel_hi:[0,1]
	v_mul_f32_e32 v50, 0xbfb8aa3b, v70
	v_fma_f32 v51, v70, s43, -v50
	v_rndne_f32_e32 v52, v50
	v_fmac_f32_e32 v51, 0xb2a5705f, v70
	v_sub_f32_e32 v50, v50, v52
	v_add_f32_e32 v50, v50, v51
	v_exp_f32_e32 v50, v50
	v_cvt_i32_f32_e32 v51, v52
	v_ldexp_f32 v50, v50, v51
	v_mul_f32_e32 v51, 0xbfb8aa3b, v71
	v_fma_f32 v52, v71, s43, -v51
	v_rndne_f32_e32 v53, v51
	v_fmac_f32_e32 v52, 0xb2a5705f, v71
	v_sub_f32_e32 v51, v51, v53
	v_add_f32_e32 v51, v51, v52
	v_exp_f32_e32 v51, v51
	v_cvt_i32_f32_e32 v52, v53
	v_cndmask_b32_e32 v50, 0, v50, vcc
	v_cmp_ngt_f32_e32 vcc, s35, v70
	v_ldexp_f32 v51, v51, v52
	s_nop 0
	v_cndmask_b32_e32 v50, v179, v50, vcc
	v_cmp_nlt_f32_e32 vcc, s34, v71
	v_pk_fma_f32 v[52:53], v[62:63], v[124:125], v[74:75] op_sel_hi:[1,0,1]
	s_nop 0
	v_cndmask_b32_e32 v51, 0, v51, vcc
	v_cmp_ngt_f32_e32 vcc, s35, v71
	s_nop 1
	v_cndmask_b32_e32 v51, v179, v51, vcc
	v_pk_add_f32 v[50:51], v[50:51], 1.0 op_sel_hi:[1,0]
	s_nop 0
	v_div_scale_f32 v54, s[2:3], v51, v51, v71
	v_rcp_f32_e32 v55, v54
	s_nop 0
	v_fma_f32 v56, -v54, v55, 1.0
	v_fmac_f32_e32 v55, v56, v55
	v_div_scale_f32 v56, vcc, v71, v51, v71
	v_mul_f32_e32 v57, v56, v55
	v_fma_f32 v58, -v54, v57, v56
	v_fmac_f32_e32 v57, v58, v55
	v_fma_f32 v54, -v54, v57, v56
	v_div_fmas_f32 v54, v54, v55, v57
	v_div_fixup_f32 v51, v54, v51, v71
	v_div_scale_f32 v54, s[2:3], v50, v50, v70
	v_rcp_f32_e32 v55, v54
	s_nop 0
	v_fma_f32 v56, -v54, v55, 1.0
	v_fmac_f32_e32 v55, v56, v55
	v_div_scale_f32 v56, vcc, v70, v50, v70
	v_mul_f32_e32 v57, v56, v55
	v_fma_f32 v58, -v54, v57, v56
	v_fmac_f32_e32 v57, v58, v55
	v_fma_f32 v54, -v54, v57, v56
	v_div_fmas_f32 v54, v54, v55, v57
	v_div_fixup_f32 v50, v54, v50, v70
	v_pk_mul_f32 v[122:123], v[52:53], v[50:51]
	s_nop 0
	v_pk_fma_f32 v[48:49], v[122:123], v[122:123], v[48:49]
	v_mul_f32_e32 v50, v123, v123
	v_pk_add_f32 v[126:127], v[50:51], v[48:49] op_sel_hi:[0,1]
	s_waitcnt vmcnt(7)
	v_pk_fma_f32 v[32:33], v[32:33], v[124:125], v[186:187] op_sel_hi:[1,0,1]
	s_waitcnt vmcnt(6)
	v_mul_f32_e32 v103, 0xbfb8aa3b, v190
	v_fma_f32 v105, v190, s43, -v103
	v_rndne_f32_e32 v107, v103
	v_fmac_f32_e32 v105, 0xb2a5705f, v190
	v_sub_f32_e32 v103, v103, v107
	v_add_f32_e32 v103, v103, v105
	v_exp_f32_e32 v103, v103
	v_cvt_i32_f32_e32 v105, v107
	v_cmp_nlt_f32_e32 vcc, s34, v190
	v_ldexp_f32 v103, v103, v105
	s_nop 0
	v_cndmask_b32_e32 v103, 0, v103, vcc
	v_cmp_ngt_f32_e32 vcc, s35, v190
	s_nop 1
	v_cndmask_b32_e32 v128, v179, v103, vcc
	v_mul_f32_e32 v103, 0xbfb8aa3b, v191
	v_fma_f32 v105, v191, s43, -v103
	v_rndne_f32_e32 v107, v103
	v_fmac_f32_e32 v105, 0xb2a5705f, v191
	v_sub_f32_e32 v103, v103, v107
	v_add_f32_e32 v103, v103, v105
	v_exp_f32_e32 v103, v103
	v_cvt_i32_f32_e32 v105, v107
	v_cmp_nlt_f32_e32 vcc, s34, v191
	v_ldexp_f32 v103, v103, v105
	s_nop 0
	v_cndmask_b32_e32 v103, 0, v103, vcc
	v_cmp_ngt_f32_e32 vcc, s35, v191
	s_nop 1
	v_cndmask_b32_e32 v129, v179, v103, vcc
	v_pk_add_f32 v[68:69], v[128:129], 1.0 op_sel_hi:[1,0]
	s_nop 0
	v_div_scale_f32 v103, s[2:3], v69, v69, v191
	v_rcp_f32_e32 v105, v103
	s_nop 0
	v_fma_f32 v107, -v103, v105, 1.0
	v_fmac_f32_e32 v105, v107, v105
	v_div_scale_f32 v107, vcc, v191, v69, v191
	v_mul_f32_e32 v109, v107, v105
	v_fma_f32 v125, -v103, v109, v107
	v_fmac_f32_e32 v109, v125, v105
	v_fma_f32 v103, -v103, v109, v107
	v_div_fmas_f32 v103, v103, v105, v109
	v_div_fixup_f32 v65, v103, v69, v191
	v_div_scale_f32 v69, s[2:3], v68, v68, v190
	v_rcp_f32_e32 v103, v69
	v_pk_fma_f32 v[34:35], v[34:35], v[124:125], v[188:189] op_sel_hi:[1,0,1]
	s_waitcnt vmcnt(5)
	v_pk_fma_f32 v[36:37], v[36:37], v[124:125], v[194:195] op_sel_hi:[1,0,1]
	v_fma_f32 v105, -v69, v103, 1.0
	v_fmac_f32_e32 v103, v105, v103
	v_div_scale_f32 v105, vcc, v190, v68, v190
	v_mul_f32_e32 v107, v105, v103
	v_fma_f32 v109, -v69, v107, v105
	v_fmac_f32_e32 v107, v109, v103
	v_fma_f32 v69, -v69, v107, v105
	v_div_fmas_f32 v69, v69, v103, v107
	v_div_fixup_f32 v64, v69, v68, v190
	v_pk_mul_f32 v[64:65], v[32:33], v[64:65]
	v_cmp_nlt_f32_e32 vcc, s34, v192
	v_pk_fma_f32 v[32:33], v[64:65], v[64:65], v[126:127]
	v_mul_f32_e32 v68, v65, v65
	v_pk_add_f32 v[32:33], v[68:69], v[32:33] op_sel_hi:[0,1]
	v_mul_f32_e32 v68, 0xbfb8aa3b, v192
	v_fma_f32 v69, v192, s43, -v68
	v_rndne_f32_e32 v103, v68
	v_fmac_f32_e32 v69, 0xb2a5705f, v192
	v_sub_f32_e32 v68, v68, v103
	v_add_f32_e32 v68, v68, v69
	v_exp_f32_e32 v68, v68
	v_cvt_i32_f32_e32 v69, v103
	v_ldexp_f32 v68, v68, v69
	v_mul_f32_e32 v69, 0xbfb8aa3b, v193
	v_fma_f32 v103, v193, s43, -v69
	v_rndne_f32_e32 v105, v69
	v_fmac_f32_e32 v103, 0xb2a5705f, v193
	v_sub_f32_e32 v69, v69, v105
	v_add_f32_e32 v69, v69, v103
	v_exp_f32_e32 v69, v69
	v_cvt_i32_f32_e32 v103, v105
	v_cndmask_b32_e32 v68, 0, v68, vcc
	v_cmp_ngt_f32_e32 vcc, s35, v192
	v_ldexp_f32 v69, v69, v103
	s_nop 0
	v_cndmask_b32_e32 v68, v179, v68, vcc
	v_cmp_nlt_f32_e32 vcc, s34, v193
	s_nop 1
	v_cndmask_b32_e32 v69, 0, v69, vcc
	v_cmp_ngt_f32_e32 vcc, s35, v193
	s_nop 1
	v_cndmask_b32_e32 v69, v179, v69, vcc
	v_pk_add_f32 v[68:69], v[68:69], 1.0 op_sel_hi:[1,0]
	s_nop 0
	v_div_scale_f32 v70, s[2:3], v69, v69, v193
	v_rcp_f32_e32 v71, v70
	s_nop 0
	v_fma_f32 v103, -v70, v71, 1.0
	v_fmac_f32_e32 v71, v103, v71
	v_div_scale_f32 v103, vcc, v193, v69, v193
	v_mul_f32_e32 v105, v103, v71
	v_fma_f32 v107, -v70, v105, v103
	v_fmac_f32_e32 v105, v107, v71
	v_fma_f32 v70, -v70, v105, v103
	v_div_fmas_f32 v70, v70, v71, v105
	v_div_fixup_f32 v67, v70, v69, v193
	v_div_scale_f32 v69, s[2:3], v68, v68, v192
	v_rcp_f32_e32 v70, v69
	s_nop 0
	v_fma_f32 v71, -v69, v70, 1.0
	v_fmac_f32_e32 v70, v71, v70
	v_div_scale_f32 v71, vcc, v192, v68, v192
	v_mul_f32_e32 v103, v71, v70
	v_fma_f32 v105, -v69, v103, v71
	v_fmac_f32_e32 v103, v105, v70
	v_fma_f32 v69, -v69, v103, v71
	v_div_fmas_f32 v69, v69, v70, v103
	v_div_fixup_f32 v66, v69, v68, v192
	v_pk_mul_f32 v[66:67], v[34:35], v[66:67]
	s_waitcnt vmcnt(4)
	v_cmp_nlt_f32_e32 vcc, s34, v198
	v_pk_fma_f32 v[32:33], v[66:67], v[66:67], v[32:33]
	v_mul_f32_e32 v34, v67, v67
	v_pk_add_f32 v[32:33], v[34:35], v[32:33] op_sel_hi:[0,1]
	v_mul_f32_e32 v34, 0xbfb8aa3b, v198
	v_fma_f32 v35, v198, s43, -v34
	v_rndne_f32_e32 v68, v34
	v_fmac_f32_e32 v35, 0xb2a5705f, v198
	v_sub_f32_e32 v34, v34, v68
	v_add_f32_e32 v34, v34, v35
	v_exp_f32_e32 v34, v34
	v_cvt_i32_f32_e32 v35, v68
	v_ldexp_f32 v34, v34, v35
	v_mul_f32_e32 v35, 0xbfb8aa3b, v199
	v_fma_f32 v68, v199, s43, -v35
	v_rndne_f32_e32 v69, v35
	v_fmac_f32_e32 v68, 0xb2a5705f, v199
	v_sub_f32_e32 v35, v35, v69
	v_add_f32_e32 v35, v35, v68
	v_exp_f32_e32 v35, v35
	v_cvt_i32_f32_e32 v68, v69
	v_cndmask_b32_e32 v34, 0, v34, vcc
	v_cmp_ngt_f32_e32 vcc, s35, v198
	v_ldexp_f32 v35, v35, v68
	s_nop 0
	v_cndmask_b32_e32 v34, v179, v34, vcc
	v_cmp_nlt_f32_e32 vcc, s34, v199
	s_nop 1
	v_cndmask_b32_e32 v35, 0, v35, vcc
	v_cmp_ngt_f32_e32 vcc, s35, v199
	s_nop 1
	v_cndmask_b32_e32 v35, v179, v35, vcc
	v_pk_add_f32 v[34:35], v[34:35], 1.0 op_sel_hi:[1,0]
	s_nop 0
	v_div_scale_f32 v60, s[2:3], v35, v35, v199
	v_rcp_f32_e32 v61, v60
	s_nop 0
	v_fma_f32 v68, -v60, v61, 1.0
	v_fmac_f32_e32 v61, v68, v61
	v_div_scale_f32 v68, vcc, v199, v35, v199
	v_mul_f32_e32 v69, v68, v61
	v_fma_f32 v70, -v60, v69, v68
	v_fmac_f32_e32 v69, v70, v61
	v_fma_f32 v60, -v60, v69, v68
	v_div_fmas_f32 v60, v60, v61, v69
	v_div_fixup_f32 v35, v60, v35, v199
	v_div_scale_f32 v57, s[2:3], v34, v34, v198
	v_rcp_f32_e32 v60, v57
	s_nop 0
	v_fma_f32 v61, -v57, v60, 1.0
	v_fmac_f32_e32 v60, v61, v60
	v_div_scale_f32 v61, vcc, v198, v34, v198
	v_mul_f32_e32 v68, v61, v60
	v_fma_f32 v69, -v57, v68, v61
	v_fmac_f32_e32 v68, v69, v60
	v_fma_f32 v57, -v57, v68, v61
	v_div_fmas_f32 v57, v57, v60, v68
	v_div_fixup_f32 v34, v57, v34, v198
	v_pk_mul_f32 v[56:57], v[36:37], v[34:35]
	v_cmp_nlt_f32_e32 vcc, s34, v200
	v_pk_fma_f32 v[32:33], v[56:57], v[56:57], v[32:33]
	v_mul_f32_e32 v34, v57, v57
	v_pk_add_f32 v[32:33], v[34:35], v[32:33] op_sel_hi:[0,1]
	v_mul_f32_e32 v34, 0xbfb8aa3b, v200
	v_fma_f32 v35, v200, s43, -v34
	v_rndne_f32_e32 v36, v34
	v_fmac_f32_e32 v35, 0xb2a5705f, v200
	v_sub_f32_e32 v34, v34, v36
	v_add_f32_e32 v34, v34, v35
	v_exp_f32_e32 v34, v34
	v_cvt_i32_f32_e32 v35, v36
	v_ldexp_f32 v34, v34, v35
	v_mul_f32_e32 v35, 0xbfb8aa3b, v201
	v_fma_f32 v36, v201, s43, -v35
	v_rndne_f32_e32 v37, v35
	v_fmac_f32_e32 v36, 0xb2a5705f, v201
	v_sub_f32_e32 v35, v35, v37
	v_add_f32_e32 v35, v35, v36
	v_exp_f32_e32 v35, v35
	v_cvt_i32_f32_e32 v36, v37
	v_cndmask_b32_e32 v34, 0, v34, vcc
	v_cmp_ngt_f32_e32 vcc, s35, v200
	v_ldexp_f32 v35, v35, v36
	s_nop 0
	v_cndmask_b32_e32 v34, v179, v34, vcc
	v_cmp_nlt_f32_e32 vcc, s34, v201
	v_pk_fma_f32 v[36:37], v[38:39], v[124:125], v[196:197] op_sel_hi:[1,0,1]
	s_nop 0
	v_cndmask_b32_e32 v35, 0, v35, vcc
	v_cmp_ngt_f32_e32 vcc, s35, v201
	s_nop 1
	v_cndmask_b32_e32 v35, v179, v35, vcc
	v_pk_add_f32 v[34:35], v[34:35], 1.0 op_sel_hi:[1,0]
	s_nop 0
	v_div_scale_f32 v38, s[2:3], v35, v35, v201
	v_rcp_f32_e32 v39, v38
	s_nop 0
	v_fma_f32 v60, -v38, v39, 1.0
	v_fmac_f32_e32 v39, v60, v39
	v_div_scale_f32 v60, vcc, v201, v35, v201
	v_mul_f32_e32 v61, v60, v39
	v_fma_f32 v62, -v38, v61, v60
	v_fmac_f32_e32 v61, v62, v39
	v_fma_f32 v38, -v38, v61, v60
	v_div_fmas_f32 v38, v38, v39, v61
	v_div_fixup_f32 v35, v38, v35, v201
	v_div_scale_f32 v38, s[2:3], v34, v34, v200
	v_rcp_f32_e32 v39, v38
	s_nop 0
	v_fma_f32 v59, -v38, v39, 1.0
	v_fmac_f32_e32 v39, v59, v39
	v_div_scale_f32 v59, vcc, v200, v34, v200
	v_mul_f32_e32 v60, v59, v39
	v_fma_f32 v61, -v38, v60, v59
	v_fmac_f32_e32 v60, v61, v39
	v_fma_f32 v38, -v38, v60, v59
	v_div_fmas_f32 v38, v38, v39, v60
	v_div_fixup_f32 v34, v38, v34, v200
	v_pk_mul_f32 v[58:59], v[36:37], v[34:35]
	s_waitcnt vmcnt(2)
	v_cmp_nlt_f32_e32 vcc, s34, v206
	v_pk_fma_f32 v[32:33], v[58:59], v[58:59], v[32:33]
	v_mul_f32_e32 v34, v59, v59
	v_pk_add_f32 v[32:33], v[34:35], v[32:33] op_sel_hi:[0,1]
	v_mul_f32_e32 v34, 0xbfb8aa3b, v206
	v_fma_f32 v35, v206, s43, -v34
	v_rndne_f32_e32 v36, v34
	v_fmac_f32_e32 v35, 0xb2a5705f, v206
	v_sub_f32_e32 v34, v34, v36
	v_add_f32_e32 v34, v34, v35
	v_exp_f32_e32 v34, v34
	v_cvt_i32_f32_e32 v35, v36
	v_ldexp_f32 v34, v34, v35
	v_mul_f32_e32 v35, 0xbfb8aa3b, v207
	v_fma_f32 v36, v207, s43, -v35
	v_rndne_f32_e32 v37, v35
	v_fmac_f32_e32 v36, 0xb2a5705f, v207
	v_sub_f32_e32 v35, v35, v37
	v_add_f32_e32 v35, v35, v36
	v_exp_f32_e32 v35, v35
	v_cvt_i32_f32_e32 v36, v37
	v_cndmask_b32_e32 v34, 0, v34, vcc
	v_cmp_ngt_f32_e32 vcc, s35, v206
	v_ldexp_f32 v35, v35, v36
	s_nop 0
	v_cndmask_b32_e32 v34, v179, v34, vcc
	v_cmp_nlt_f32_e32 vcc, s34, v207
	v_pk_fma_f32 v[36:37], v[40:41], v[124:125], v[202:203] op_sel_hi:[1,0,1]
	s_nop 0
	v_cndmask_b32_e32 v35, 0, v35, vcc
	v_cmp_ngt_f32_e32 vcc, s35, v207
	s_nop 1
	v_cndmask_b32_e32 v35, v179, v35, vcc
	v_pk_add_f32 v[34:35], v[34:35], 1.0 op_sel_hi:[1,0]
	s_nop 0
	v_div_scale_f32 v38, s[2:3], v35, v35, v207
	v_rcp_f32_e32 v39, v38
	s_nop 0
	v_fma_f32 v40, -v38, v39, 1.0
	v_fmac_f32_e32 v39, v40, v39
	v_div_scale_f32 v40, vcc, v207, v35, v207
	v_mul_f32_e32 v41, v40, v39
	v_fma_f32 v52, -v38, v41, v40
	v_fmac_f32_e32 v41, v52, v39
	v_fma_f32 v38, -v38, v41, v40
	v_div_fmas_f32 v38, v38, v39, v41
	v_div_fixup_f32 v35, v38, v35, v207
	v_div_scale_f32 v38, s[2:3], v34, v34, v206
	v_rcp_f32_e32 v39, v38
	s_nop 0
	v_fma_f32 v40, -v38, v39, 1.0
	v_fmac_f32_e32 v39, v40, v39
	v_div_scale_f32 v40, vcc, v206, v34, v206
	v_mul_f32_e32 v41, v40, v39
	v_fma_f32 v49, -v38, v41, v40
	v_fmac_f32_e32 v41, v49, v39
	v_fma_f32 v38, -v38, v41, v40
	v_div_fmas_f32 v38, v38, v39, v41
	v_div_fixup_f32 v34, v38, v34, v206
	v_pk_mul_f32 v[48:49], v[36:37], v[34:35]
	v_cmp_nlt_f32_e32 vcc, s34, v208
	v_pk_fma_f32 v[32:33], v[48:49], v[48:49], v[32:33]
	v_mul_f32_e32 v34, v49, v49
	v_pk_add_f32 v[32:33], v[34:35], v[32:33] op_sel_hi:[0,1]
	v_mul_f32_e32 v34, 0xbfb8aa3b, v208
	v_fma_f32 v35, v208, s43, -v34
	v_rndne_f32_e32 v36, v34
	v_fmac_f32_e32 v35, 0xb2a5705f, v208
	v_sub_f32_e32 v34, v34, v36
	v_add_f32_e32 v34, v34, v35
	v_exp_f32_e32 v34, v34
	v_cvt_i32_f32_e32 v35, v36
	v_ldexp_f32 v34, v34, v35
	v_mul_f32_e32 v35, 0xbfb8aa3b, v209
	v_fma_f32 v36, v209, s43, -v35
	v_rndne_f32_e32 v37, v35
	v_fmac_f32_e32 v36, 0xb2a5705f, v209
	v_sub_f32_e32 v35, v35, v37
	v_add_f32_e32 v35, v35, v36
	v_exp_f32_e32 v35, v35
	v_cvt_i32_f32_e32 v36, v37
	v_cndmask_b32_e32 v34, 0, v34, vcc
	v_cmp_ngt_f32_e32 vcc, s35, v208
	v_ldexp_f32 v35, v35, v36
	s_nop 0
	v_cndmask_b32_e32 v34, v179, v34, vcc
	v_cmp_nlt_f32_e32 vcc, s34, v209
	v_pk_fma_f32 v[36:37], v[42:43], v[124:125], v[204:205] op_sel_hi:[1,0,1]
	s_nop 0
	v_cndmask_b32_e32 v35, 0, v35, vcc
	v_cmp_ngt_f32_e32 vcc, s35, v209
	s_nop 1
	v_cndmask_b32_e32 v35, v179, v35, vcc
	v_pk_add_f32 v[34:35], v[34:35], 1.0 op_sel_hi:[1,0]
	s_nop 0
	v_div_scale_f32 v38, s[2:3], v35, v35, v209
	v_rcp_f32_e32 v39, v38
	s_nop 0
	v_fma_f32 v40, -v38, v39, 1.0
	v_fmac_f32_e32 v39, v40, v39
	v_div_scale_f32 v40, vcc, v209, v35, v209
	v_mul_f32_e32 v41, v40, v39
	v_fma_f32 v42, -v38, v41, v40
	v_fmac_f32_e32 v41, v42, v39
	v_fma_f32 v38, -v38, v41, v40
	v_div_fmas_f32 v38, v38, v39, v41
	v_div_fixup_f32 v35, v38, v35, v209
	v_div_scale_f32 v38, s[2:3], v34, v34, v208
	v_rcp_f32_e32 v39, v38
	s_nop 0
	v_fma_f32 v40, -v38, v39, 1.0
	v_fmac_f32_e32 v39, v40, v39
	v_div_scale_f32 v40, vcc, v208, v34, v208
	v_mul_f32_e32 v41, v40, v39
	v_fma_f32 v42, -v38, v41, v40
	v_fmac_f32_e32 v41, v42, v39
	v_fma_f32 v38, -v38, v41, v40
	v_div_fmas_f32 v38, v38, v39, v41
	v_div_fixup_f32 v34, v38, v34, v208
	v_pk_mul_f32 v[52:53], v[36:37], v[34:35]
	s_waitcnt vmcnt(0)
	v_cmp_nlt_f32_e32 vcc, s34, v214
	v_pk_fma_f32 v[32:33], v[52:53], v[52:53], v[32:33]
	v_mul_f32_e32 v34, v53, v53
	v_pk_add_f32 v[32:33], v[34:35], v[32:33] op_sel_hi:[0,1]
	v_mul_f32_e32 v34, 0xbfb8aa3b, v214
	v_fma_f32 v35, v214, s43, -v34
	v_rndne_f32_e32 v36, v34
	v_fmac_f32_e32 v35, 0xb2a5705f, v214
	v_sub_f32_e32 v34, v34, v36
	v_add_f32_e32 v34, v34, v35
	v_exp_f32_e32 v34, v34
	v_cvt_i32_f32_e32 v35, v36
	v_ldexp_f32 v34, v34, v35
	v_mul_f32_e32 v35, 0xbfb8aa3b, v215
	v_fma_f32 v36, v215, s43, -v35
	v_rndne_f32_e32 v37, v35
	v_fmac_f32_e32 v36, 0xb2a5705f, v215
	v_sub_f32_e32 v35, v35, v37
	v_add_f32_e32 v35, v35, v36
	v_exp_f32_e32 v35, v35
	v_cvt_i32_f32_e32 v36, v37
	v_cndmask_b32_e32 v34, 0, v34, vcc
	v_cmp_ngt_f32_e32 vcc, s35, v214
	v_ldexp_f32 v35, v35, v36
	s_nop 0
	v_cndmask_b32_e32 v34, v179, v34, vcc
	v_cmp_nlt_f32_e32 vcc, s34, v215
	v_pk_fma_f32 v[36:37], v[44:45], v[124:125], v[210:211] op_sel_hi:[1,0,1]
	s_nop 0
	v_cndmask_b32_e32 v35, 0, v35, vcc
	v_cmp_ngt_f32_e32 vcc, s35, v215
	s_nop 1
	v_cndmask_b32_e32 v35, v179, v35, vcc
	v_pk_add_f32 v[34:35], v[34:35], 1.0 op_sel_hi:[1,0]
	s_nop 0
	v_div_scale_f32 v38, s[2:3], v35, v35, v215
	v_rcp_f32_e32 v39, v38
	s_nop 0
	v_fma_f32 v40, -v38, v39, 1.0
	v_fmac_f32_e32 v39, v40, v39
	v_div_scale_f32 v40, vcc, v215, v35, v215
	v_mul_f32_e32 v41, v40, v39
	v_fma_f32 v42, -v38, v41, v40
	v_fmac_f32_e32 v41, v42, v39
	v_fma_f32 v38, -v38, v41, v40
	v_div_fmas_f32 v38, v38, v39, v41
	v_div_fixup_f32 v35, v38, v35, v215
	v_div_scale_f32 v38, s[2:3], v34, v34, v214
	v_rcp_f32_e32 v39, v38
	s_nop 0
	v_fma_f32 v40, -v38, v39, 1.0
	v_fmac_f32_e32 v39, v40, v39
	v_div_scale_f32 v40, vcc, v214, v34, v214
	v_mul_f32_e32 v41, v40, v39
	v_fma_f32 v42, -v38, v41, v40
	v_fmac_f32_e32 v41, v42, v39
	v_fma_f32 v38, -v38, v41, v40
	v_div_fmas_f32 v38, v38, v39, v41
	v_div_fixup_f32 v34, v38, v34, v214
	v_pk_mul_f32 v[60:61], v[36:37], v[34:35]
	v_cmp_nlt_f32_e32 vcc, s34, v216
	v_pk_fma_f32 v[32:33], v[60:61], v[60:61], v[32:33]
	v_mul_f32_e32 v34, v61, v61
	v_pk_add_f32 v[32:33], v[34:35], v[32:33] op_sel_hi:[0,1]
	v_mul_f32_e32 v34, 0xbfb8aa3b, v216
	v_fma_f32 v35, v216, s43, -v34
	v_rndne_f32_e32 v36, v34
	v_fmac_f32_e32 v35, 0xb2a5705f, v216
	v_sub_f32_e32 v34, v34, v36
	v_add_f32_e32 v34, v34, v35
	v_exp_f32_e32 v34, v34
	v_cvt_i32_f32_e32 v35, v36
	v_ldexp_f32 v34, v34, v35
	v_mul_f32_e32 v35, 0xbfb8aa3b, v217
	v_fma_f32 v36, v217, s43, -v35
	v_rndne_f32_e32 v37, v35
	v_fmac_f32_e32 v36, 0xb2a5705f, v217
	v_sub_f32_e32 v35, v35, v37
	v_add_f32_e32 v35, v35, v36
	v_exp_f32_e32 v35, v35
	v_cvt_i32_f32_e32 v36, v37
	v_cndmask_b32_e32 v34, 0, v34, vcc
	v_cmp_ngt_f32_e32 vcc, s35, v216
	v_ldexp_f32 v35, v35, v36
	s_nop 0
	v_cndmask_b32_e32 v34, v179, v34, vcc
	v_cmp_nlt_f32_e32 vcc, s34, v217
	v_pk_fma_f32 v[36:37], v[46:47], v[124:125], v[212:213] op_sel_hi:[1,0,1]
	s_nop 0
	v_cndmask_b32_e32 v35, 0, v35, vcc
	v_cmp_ngt_f32_e32 vcc, s35, v217
	s_nop 1
	v_cndmask_b32_e32 v35, v179, v35, vcc
	v_pk_add_f32 v[34:35], v[34:35], 1.0 op_sel_hi:[1,0]
	s_nop 0
	v_div_scale_f32 v38, s[2:3], v35, v35, v217
	v_rcp_f32_e32 v39, v38
	s_nop 0
	v_fma_f32 v40, -v38, v39, 1.0
	v_fmac_f32_e32 v39, v40, v39
	v_div_scale_f32 v40, vcc, v217, v35, v217
	v_mul_f32_e32 v41, v40, v39
	v_fma_f32 v42, -v38, v41, v40
	v_fmac_f32_e32 v41, v42, v39
	v_fma_f32 v38, -v38, v41, v40
	v_div_fmas_f32 v38, v38, v39, v41
	v_div_fixup_f32 v35, v38, v35, v217
	v_div_scale_f32 v38, s[2:3], v34, v34, v216
	v_rcp_f32_e32 v39, v38
	s_nop 0
	v_fma_f32 v40, -v38, v39, 1.0
	v_fmac_f32_e32 v39, v40, v39
	v_div_scale_f32 v40, vcc, v216, v34, v216
	v_mul_f32_e32 v41, v40, v39
	v_fma_f32 v42, -v38, v41, v40
	v_fmac_f32_e32 v41, v42, v39
	v_fma_f32 v38, -v38, v41, v40
	v_div_fmas_f32 v38, v38, v39, v41
	v_div_fixup_f32 v34, v38, v34, v216
	v_pk_mul_f32 v[78:79], v[36:37], v[34:35]
	s_nop 0
	v_pk_fma_f32 v[32:33], v[78:79], v[78:79], v[32:33]
	v_mul_f32_e32 v34, v79, v79
	v_pk_add_f32 v[32:33], v[34:35], v[32:33] op_sel_hi:[0,1]
	v_mov_b32_e32 v33, v32
	s_nop 1
	v_permlane32_swap_b32_e32 v32, v33
	s_and_saveexec_b64 s[14:15], s[48:49]
	v_add_f32_e32 v32, v32, v33
	ds_write_b32 v97, v32
	s_or_b64 exec, exec, s[14:15]
	v_mov_b32_e32 v33, s5
	v_or_b32_e32 v32, s4, v92
	v_lshlrev_b64 v[34:35], 5, v[32:33]
	v_lshl_add_u64 v[34:35], s[8:9], 0, v[34:35]
	global_load_dword v143, v[34:35], off
	v_mad_u64_u32 v[132:133], s[2:3], v32, s42, v[98:99]
	v_lshlrev_b64 v[50:51], 11, v[32:33]
	s_mul_i32 s2, s5, 0x2800
	v_lshl_add_u64 v[130:131], v[94:95], 0, v[50:51]
	v_add_u32_e32 v133, s2, v133
	global_load_dwordx4 v[70:73], v[130:131], off
	global_load_dwordx4 v[74:77], v[132:133], off
	global_load_dwordx4 v[134:137], v[130:131], off offset:32
	global_load_dwordx4 v[138:141], v[132:133], off offset:32
	global_load_dwordx4 v[44:47], v[130:131], off offset:64
	global_load_dwordx4 v[40:43], v[132:133], off offset:64
	global_load_dwordx4 v[36:39], v[130:131], off offset:96
	global_load_dwordx4 v[32:35], v[132:133], off offset:96
	global_load_dwordx4 v[186:189], v[130:131], off offset:128
	global_load_dwordx4 v[190:193], v[132:133], off offset:128
	global_load_dwordx4 v[194:197], v[130:131], off offset:160
	global_load_dwordx4 v[198:201], v[132:133], off offset:160
	global_load_dwordx4 v[202:205], v[130:131], off offset:192
	global_load_dwordx4 v[206:209], v[132:133], off offset:192
	global_load_dwordx4 v[210:213], v[130:131], off offset:224
	global_load_dwordx4 v[214:217], v[132:133], off offset:224
	s_waitcnt vmcnt(16)
	v_exp_f32_e32 v126, v143
	s_waitcnt vmcnt(15)
	v_pk_fma_f32 v[16:17], v[16:17], v[126:127], v[70:71] op_sel_hi:[1,0,1]
	v_pk_fma_f32 v[18:19], v[18:19], v[126:127], v[72:73] op_sel_hi:[1,0,1]
	s_waitcnt vmcnt(14)
	v_mul_f32_e32 v54, 0xbfb8aa3b, v74
	v_fma_f32 v55, v74, s43, -v54
	v_rndne_f32_e32 v62, v54
	v_fmac_f32_e32 v55, 0xb2a5705f, v74
	v_sub_f32_e32 v54, v54, v62
	v_add_f32_e32 v54, v54, v55
	v_exp_f32_e32 v54, v54
	v_cvt_i32_f32_e32 v55, v62
	v_cmp_nlt_f32_e32 vcc, s34, v74
	s_waitcnt vmcnt(13)
	v_pk_fma_f32 v[20:21], v[20:21], v[126:127], v[134:135] op_sel_hi:[1,0,1]
	v_ldexp_f32 v54, v54, v55
	v_mul_f32_e32 v55, 0xbfb8aa3b, v75
	v_fma_f32 v62, v75, s43, -v55
	v_rndne_f32_e32 v63, v55
	v_fmac_f32_e32 v62, 0xb2a5705f, v75
	v_sub_f32_e32 v55, v55, v63
	v_add_f32_e32 v55, v55, v62
	v_exp_f32_e32 v55, v55
	v_cvt_i32_f32_e32 v62, v63
	v_cndmask_b32_e32 v54, 0, v54, vcc
	v_cmp_ngt_f32_e32 vcc, s35, v74
	v_ldexp_f32 v55, v55, v62
	s_nop 0
	v_cndmask_b32_e32 v54, v179, v54, vcc
	v_cmp_nlt_f32_e32 vcc, s34, v75
	s_nop 1
	v_cndmask_b32_e32 v55, 0, v55, vcc
	v_cmp_ngt_f32_e32 vcc, s35, v75
	s_nop 1
	v_cndmask_b32_e32 v55, v179, v55, vcc
	v_pk_add_f32 v[54:55], v[54:55], 1.0 op_sel_hi:[1,0]
	s_nop 0
	v_div_scale_f32 v62, s[2:3], v55, v55, v75
	v_rcp_f32_e32 v63, v62
	s_nop 0
	v_fma_f32 v68, -v62, v63, 1.0
	v_fmac_f32_e32 v63, v68, v63
	v_div_scale_f32 v68, vcc, v75, v55, v75
	v_mul_f32_e32 v69, v68, v63
	v_fma_f32 v70, -v62, v69, v68
	v_fmac_f32_e32 v69, v70, v63
	v_fma_f32 v62, -v62, v69, v68
	v_div_fmas_f32 v62, v62, v63, v69
	v_div_fixup_f32 v55, v62, v55, v75
	v_div_scale_f32 v62, s[2:3], v54, v54, v74
	v_rcp_f32_e32 v63, v62
	s_nop 0
	v_fma_f32 v68, -v62, v63, 1.0
	v_fmac_f32_e32 v63, v68, v63
	v_div_scale_f32 v68, vcc, v74, v54, v74
	v_mul_f32_e32 v69, v68, v63
	v_fma_f32 v70, -v62, v69, v68
	v_fmac_f32_e32 v69, v70, v63
	v_fma_f32 v62, -v62, v69, v68
	v_div_fmas_f32 v62, v62, v63, v69
	v_div_fixup_f32 v54, v62, v54, v74
	v_pk_mul_f32 v[70:71], v[16:17], v[54:55]
	v_mul_f32_e32 v54, 0xbfb8aa3b, v76
	v_fma_f32 v55, v76, s43, -v54
	v_rndne_f32_e32 v62, v54
	v_fmac_f32_e32 v55, 0xb2a5705f, v76
	v_sub_f32_e32 v54, v54, v62
	v_add_f32_e32 v54, v54, v55
	v_exp_f32_e32 v54, v54
	v_cvt_i32_f32_e32 v55, v62
	v_cmp_nlt_f32_e32 vcc, s34, v76
	v_mul_f32_e32 v16, v71, v71
	v_pk_fma_f32 v[16:17], v[70:71], v[70:71], v[16:17] op_sel_hi:[1,1,0]
	v_ldexp_f32 v54, v54, v55
	v_mul_f32_e32 v55, 0xbfb8aa3b, v77
	v_fma_f32 v62, v77, s43, -v55
	v_rndne_f32_e32 v63, v55
	v_fmac_f32_e32 v62, 0xb2a5705f, v77
	v_sub_f32_e32 v55, v55, v63
	v_add_f32_e32 v55, v55, v62
	v_exp_f32_e32 v55, v55
	v_cvt_i32_f32_e32 v62, v63
	v_cndmask_b32_e32 v54, 0, v54, vcc
	v_cmp_ngt_f32_e32 vcc, s35, v76
	v_ldexp_f32 v55, v55, v62
	s_nop 0
	v_cndmask_b32_e32 v54, v179, v54, vcc
	v_cmp_nlt_f32_e32 vcc, s34, v77
	s_nop 1
	v_cndmask_b32_e32 v55, 0, v55, vcc
	v_cmp_ngt_f32_e32 vcc, s35, v77
	s_nop 1
	v_cndmask_b32_e32 v55, v179, v55, vcc
	v_pk_add_f32 v[54:55], v[54:55], 1.0 op_sel_hi:[1,0]
	s_nop 0
	v_div_scale_f32 v62, s[2:3], v55, v55, v77
	v_rcp_f32_e32 v63, v62
	s_nop 0
	v_fma_f32 v68, -v62, v63, 1.0
	v_fmac_f32_e32 v63, v68, v63
	v_div_scale_f32 v68, vcc, v77, v55, v77
	v_mul_f32_e32 v69, v68, v63
	v_fma_f32 v72, -v62, v69, v68
	v_fmac_f32_e32 v69, v72, v63
	v_fma_f32 v62, -v62, v69, v68
	v_div_fmas_f32 v62, v62, v63, v69
	v_div_fixup_f32 v55, v62, v55, v77
	v_div_scale_f32 v62, s[2:3], v54, v54, v76
	v_rcp_f32_e32 v63, v62
	s_nop 0
	v_fma_f32 v68, -v62, v63, 1.0
	v_fmac_f32_e32 v63, v68, v63
	v_div_scale_f32 v68, vcc, v76, v54, v76
	v_mul_f32_e32 v69, v68, v63
	v_fma_f32 v72, -v62, v69, v68
	v_fmac_f32_e32 v69, v72, v63
	v_fma_f32 v62, -v62, v69, v68
	v_div_fmas_f32 v62, v62, v63, v69
	v_div_fixup_f32 v54, v62, v54, v76
	v_pk_mul_f32 v[74:75], v[18:19], v[54:55]
	s_waitcnt vmcnt(12)
	v_cmp_nlt_f32_e32 vcc, s34, v138
	v_pk_fma_f32 v[16:17], v[74:75], v[74:75], v[16:17]
	v_mul_f32_e32 v18, v75, v75
	v_pk_add_f32 v[16:17], v[18:19], v[16:17] op_sel_hi:[0,1]
	v_mul_f32_e32 v18, 0xbfb8aa3b, v138
	v_fma_f32 v19, v138, s43, -v18
	v_rndne_f32_e32 v54, v18
	v_fmac_f32_e32 v19, 0xb2a5705f, v138
	v_sub_f32_e32 v18, v18, v54
	v_add_f32_e32 v18, v18, v19
	v_exp_f32_e32 v18, v18
	v_cvt_i32_f32_e32 v19, v54
	v_ldexp_f32 v18, v18, v19
	v_mul_f32_e32 v19, 0xbfb8aa3b, v139
	v_fma_f32 v54, v139, s43, -v19
	v_rndne_f32_e32 v55, v19
	v_fmac_f32_e32 v54, 0xb2a5705f, v139
	v_sub_f32_e32 v19, v19, v55
	v_add_f32_e32 v19, v19, v54
	v_exp_f32_e32 v19, v19
	v_cvt_i32_f32_e32 v54, v55
	v_cndmask_b32_e32 v18, 0, v18, vcc
	v_cmp_ngt_f32_e32 vcc, s35, v138
	v_ldexp_f32 v19, v19, v54
	s_nop 0
	v_cndmask_b32_e32 v18, v179, v18, vcc
	v_cmp_nlt_f32_e32 vcc, s34, v139
	s_nop 1
	v_cndmask_b32_e32 v19, 0, v19, vcc
	v_cmp_ngt_f32_e32 vcc, s35, v139
	s_nop 1
	v_cndmask_b32_e32 v19, v179, v19, vcc
	v_pk_add_f32 v[18:19], v[18:19], 1.0 op_sel_hi:[1,0]
	s_nop 0
	v_div_scale_f32 v54, s[2:3], v19, v19, v139
	v_rcp_f32_e32 v55, v54
	s_nop 0
	v_fma_f32 v62, -v54, v55, 1.0
	v_fmac_f32_e32 v55, v62, v55
	v_div_scale_f32 v62, vcc, v139, v19, v139
	v_mul_f32_e32 v63, v62, v55
	v_fma_f32 v68, -v54, v63, v62
	v_fmac_f32_e32 v63, v68, v55
	v_fma_f32 v54, -v54, v63, v62
	v_div_fmas_f32 v54, v54, v55, v63
	v_div_fixup_f32 v19, v54, v19, v139
	v_div_scale_f32 v54, s[2:3], v18, v18, v138
	v_rcp_f32_e32 v55, v54
	s_nop 0
	v_fma_f32 v62, -v54, v55, 1.0
	v_fmac_f32_e32 v55, v62, v55
	v_div_scale_f32 v62, vcc, v138, v18, v138
	v_mul_f32_e32 v63, v62, v55
	v_fma_f32 v68, -v54, v63, v62
	v_fmac_f32_e32 v63, v68, v55
	v_fma_f32 v54, -v54, v63, v62
	v_div_fmas_f32 v54, v54, v55, v63
	v_div_fixup_f32 v18, v54, v18, v138
	v_pk_mul_f32 v[54:55], v[20:21], v[18:19]
	v_cmp_nlt_f32_e32 vcc, s34, v140
	v_pk_fma_f32 v[16:17], v[54:55], v[54:55], v[16:17]
	v_mul_f32_e32 v18, v55, v55
	v_pk_add_f32 v[16:17], v[18:19], v[16:17] op_sel_hi:[0,1]
	v_mul_f32_e32 v18, 0xbfb8aa3b, v140
	v_fma_f32 v19, v140, s43, -v18
	v_rndne_f32_e32 v20, v18
	v_fmac_f32_e32 v19, 0xb2a5705f, v140
	v_sub_f32_e32 v18, v18, v20
	v_add_f32_e32 v18, v18, v19
	v_exp_f32_e32 v18, v18
	v_cvt_i32_f32_e32 v19, v20
	v_ldexp_f32 v18, v18, v19
	v_mul_f32_e32 v19, 0xbfb8aa3b, v141
	v_fma_f32 v20, v141, s43, -v19
	v_rndne_f32_e32 v21, v19
	v_fmac_f32_e32 v20, 0xb2a5705f, v141
	v_sub_f32_e32 v19, v19, v21
	v_add_f32_e32 v19, v19, v20
	v_exp_f32_e32 v19, v19
	v_cvt_i32_f32_e32 v20, v21
	v_cndmask_b32_e32 v18, 0, v18, vcc
	v_cmp_ngt_f32_e32 vcc, s35, v140
	v_ldexp_f32 v19, v19, v20
	s_nop 0
	v_cndmask_b32_e32 v18, v179, v18, vcc
	v_cmp_nlt_f32_e32 vcc, s34, v141
	v_pk_fma_f32 v[20:21], v[22:23], v[126:127], v[136:137] op_sel_hi:[1,0,1]
	s_nop 0
	v_cndmask_b32_e32 v19, 0, v19, vcc
	v_cmp_ngt_f32_e32 vcc, s35, v141
	s_nop 1
	v_cndmask_b32_e32 v19, v179, v19, vcc
	v_pk_add_f32 v[18:19], v[18:19], 1.0 op_sel_hi:[1,0]
	s_nop 0
	v_div_scale_f32 v22, s[2:3], v19, v19, v141
	v_rcp_f32_e32 v23, v22
	s_nop 0
	v_fma_f32 v62, -v22, v23, 1.0
	v_fmac_f32_e32 v23, v62, v23
	v_div_scale_f32 v62, vcc, v141, v19, v141
	v_mul_f32_e32 v63, v62, v23
	v_fma_f32 v68, -v22, v63, v62
	v_fmac_f32_e32 v63, v68, v23
	v_fma_f32 v22, -v22, v63, v62
	v_div_fmas_f32 v22, v22, v23, v63
	v_div_fixup_f32 v19, v22, v19, v141
	v_div_scale_f32 v22, s[2:3], v18, v18, v140
	v_rcp_f32_e32 v23, v22
	s_nop 0
	v_fma_f32 v62, -v22, v23, 1.0
	v_fmac_f32_e32 v23, v62, v23
	v_div_scale_f32 v62, vcc, v140, v18, v140
	v_mul_f32_e32 v63, v62, v23
	v_fma_f32 v68, -v22, v63, v62
	v_fmac_f32_e32 v63, v68, v23
	v_fma_f32 v22, -v22, v63, v62
	v_div_fmas_f32 v22, v22, v23, v63
	v_div_fixup_f32 v18, v22, v18, v140
	v_pk_mul_f32 v[62:63], v[20:21], v[18:19]
	s_waitcnt vmcnt(10)
	v_cmp_nlt_f32_e32 vcc, s34, v40
	v_pk_fma_f32 v[16:17], v[62:63], v[62:63], v[16:17]
	v_mul_f32_e32 v18, v63, v63
	v_pk_add_f32 v[16:17], v[18:19], v[16:17] op_sel_hi:[0,1]
	v_mul_f32_e32 v18, 0xbfb8aa3b, v40
	v_fma_f32 v19, v40, s43, -v18
	v_rndne_f32_e32 v20, v18
	v_fmac_f32_e32 v19, 0xb2a5705f, v40
	v_sub_f32_e32 v18, v18, v20
	v_add_f32_e32 v18, v18, v19
	v_exp_f32_e32 v18, v18
	v_cvt_i32_f32_e32 v19, v20
	v_ldexp_f32 v18, v18, v19
	v_mul_f32_e32 v19, 0xbfb8aa3b, v41
	v_fma_f32 v20, v41, s43, -v19
	v_rndne_f32_e32 v21, v19
	v_fmac_f32_e32 v20, 0xb2a5705f, v41
	v_sub_f32_e32 v19, v19, v21
	v_add_f32_e32 v19, v19, v20
	v_exp_f32_e32 v19, v19
	v_cvt_i32_f32_e32 v20, v21
	v_cndmask_b32_e32 v18, 0, v18, vcc
	v_cmp_ngt_f32_e32 vcc, s35, v40
	v_ldexp_f32 v19, v19, v20
	s_nop 0
	v_cndmask_b32_e32 v18, v179, v18, vcc
	v_cmp_nlt_f32_e32 vcc, s34, v41
	v_pk_fma_f32 v[20:21], v[24:25], v[126:127], v[44:45] op_sel_hi:[1,0,1]
	s_nop 0
	v_cndmask_b32_e32 v19, 0, v19, vcc
	v_cmp_ngt_f32_e32 vcc, s35, v41
	s_nop 1
	v_cndmask_b32_e32 v19, v179, v19, vcc
	v_pk_add_f32 v[18:19], v[18:19], 1.0 op_sel_hi:[1,0]
	s_nop 0
	v_div_scale_f32 v22, s[2:3], v19, v19, v41
	v_rcp_f32_e32 v23, v22
	s_nop 0
	v_fma_f32 v24, -v22, v23, 1.0
	v_fmac_f32_e32 v23, v24, v23
	v_div_scale_f32 v24, vcc, v41, v19, v41
	v_mul_f32_e32 v25, v24, v23
	v_fma_f32 v44, -v22, v25, v24
	v_fmac_f32_e32 v25, v44, v23
	v_fma_f32 v22, -v22, v25, v24
	v_div_fmas_f32 v22, v22, v23, v25
	v_div_fixup_f32 v19, v22, v19, v41
	v_div_scale_f32 v22, s[2:3], v18, v18, v40
	v_rcp_f32_e32 v23, v22
	s_nop 0
	v_fma_f32 v24, -v22, v23, 1.0
	v_fmac_f32_e32 v23, v24, v23
	v_div_scale_f32 v24, vcc, v40, v18, v40
	v_mul_f32_e32 v25, v24, v23
	v_fma_f32 v41, -v22, v25, v24
	v_fmac_f32_e32 v25, v41, v23
	v_fma_f32 v22, -v22, v25, v24
	v_div_fmas_f32 v22, v22, v23, v25
	v_div_fixup_f32 v18, v22, v18, v40
	v_pk_mul_f32 v[68:69], v[20:21], v[18:19]
	v_cmp_nlt_f32_e32 vcc, s34, v42
	v_pk_fma_f32 v[16:17], v[68:69], v[68:69], v[16:17]
	v_mul_f32_e32 v18, v69, v69
	v_pk_add_f32 v[16:17], v[18:19], v[16:17] op_sel_hi:[0,1]
	v_mul_f32_e32 v18, 0xbfb8aa3b, v42
	v_fma_f32 v19, v42, s43, -v18
	v_rndne_f32_e32 v20, v18
	v_fmac_f32_e32 v19, 0xb2a5705f, v42
	v_sub_f32_e32 v18, v18, v20
	v_add_f32_e32 v18, v18, v19
	v_exp_f32_e32 v18, v18
	v_cvt_i32_f32_e32 v19, v20
	v_ldexp_f32 v18, v18, v19
	v_mul_f32_e32 v19, 0xbfb8aa3b, v43
	v_fma_f32 v20, v43, s43, -v19
	v_rndne_f32_e32 v21, v19
	v_fmac_f32_e32 v20, 0xb2a5705f, v43
	v_sub_f32_e32 v19, v19, v21
	v_add_f32_e32 v19, v19, v20
	v_exp_f32_e32 v19, v19
	v_cvt_i32_f32_e32 v20, v21
	v_cndmask_b32_e32 v18, 0, v18, vcc
	v_cmp_ngt_f32_e32 vcc, s35, v42
	v_ldexp_f32 v19, v19, v20
	s_nop 0
	v_cndmask_b32_e32 v18, v179, v18, vcc
	v_cmp_nlt_f32_e32 vcc, s34, v43
	v_pk_fma_f32 v[20:21], v[26:27], v[126:127], v[46:47] op_sel_hi:[1,0,1]
	s_nop 0
	v_cndmask_b32_e32 v19, 0, v19, vcc
	v_cmp_ngt_f32_e32 vcc, s35, v43
	s_nop 1
	v_cndmask_b32_e32 v19, v179, v19, vcc
	v_pk_add_f32 v[18:19], v[18:19], 1.0 op_sel_hi:[1,0]
	s_nop 0
	v_div_scale_f32 v22, s[2:3], v19, v19, v43
	v_rcp_f32_e32 v23, v22
	s_nop 0
	v_fma_f32 v24, -v22, v23, 1.0
	v_fmac_f32_e32 v23, v24, v23
	v_div_scale_f32 v24, vcc, v43, v19, v43
	v_mul_f32_e32 v25, v24, v23
	v_fma_f32 v26, -v22, v25, v24
	v_fmac_f32_e32 v25, v26, v23
	v_fma_f32 v22, -v22, v25, v24
	v_div_fmas_f32 v22, v22, v23, v25
	v_div_fixup_f32 v19, v22, v19, v43
	v_div_scale_f32 v22, s[2:3], v18, v18, v42
	v_rcp_f32_e32 v23, v22
	s_nop 0
	v_fma_f32 v24, -v22, v23, 1.0
	v_fmac_f32_e32 v23, v24, v23
	v_div_scale_f32 v24, vcc, v42, v18, v42
	v_mul_f32_e32 v25, v24, v23
	v_fma_f32 v26, -v22, v25, v24
	v_fmac_f32_e32 v25, v26, v23
	v_fma_f32 v22, -v22, v25, v24
	v_div_fmas_f32 v22, v22, v23, v25
	v_div_fixup_f32 v18, v22, v18, v42
	v_pk_mul_f32 v[72:73], v[20:21], v[18:19]
	s_waitcnt vmcnt(8)
	v_cmp_nlt_f32_e32 vcc, s34, v32
	v_pk_fma_f32 v[16:17], v[72:73], v[72:73], v[16:17]
	v_mul_f32_e32 v18, v73, v73
	v_pk_add_f32 v[16:17], v[18:19], v[16:17] op_sel_hi:[0,1]
	v_mul_f32_e32 v18, 0xbfb8aa3b, v32
	v_fma_f32 v19, v32, s43, -v18
	v_rndne_f32_e32 v20, v18
	v_fmac_f32_e32 v19, 0xb2a5705f, v32
	v_sub_f32_e32 v18, v18, v20
	v_add_f32_e32 v18, v18, v19
	v_exp_f32_e32 v18, v18
	v_cvt_i32_f32_e32 v19, v20
	v_ldexp_f32 v18, v18, v19
	v_mul_f32_e32 v19, 0xbfb8aa3b, v33
	v_fma_f32 v20, v33, s43, -v19
	v_rndne_f32_e32 v21, v19
	v_fmac_f32_e32 v20, 0xb2a5705f, v33
	v_sub_f32_e32 v19, v19, v21
	v_add_f32_e32 v19, v19, v20
	v_exp_f32_e32 v19, v19
	v_cvt_i32_f32_e32 v20, v21
	v_cndmask_b32_e32 v18, 0, v18, vcc
	v_cmp_ngt_f32_e32 vcc, s35, v32
	v_ldexp_f32 v19, v19, v20
	s_nop 0
	v_cndmask_b32_e32 v18, v179, v18, vcc
	v_cmp_nlt_f32_e32 vcc, s34, v33
	v_pk_fma_f32 v[20:21], v[28:29], v[126:127], v[36:37] op_sel_hi:[1,0,1]
	s_nop 0
	v_cndmask_b32_e32 v19, 0, v19, vcc
	v_cmp_ngt_f32_e32 vcc, s35, v33
	s_nop 1
	v_cndmask_b32_e32 v19, v179, v19, vcc
	v_pk_add_f32 v[18:19], v[18:19], 1.0 op_sel_hi:[1,0]
	s_nop 0
	v_div_scale_f32 v22, s[2:3], v19, v19, v33
	v_rcp_f32_e32 v23, v22
	s_nop 0
	v_fma_f32 v24, -v22, v23, 1.0
	v_fmac_f32_e32 v23, v24, v23
	v_div_scale_f32 v24, vcc, v33, v19, v33
	v_mul_f32_e32 v25, v24, v23
	v_fma_f32 v26, -v22, v25, v24
	v_fmac_f32_e32 v25, v26, v23
	v_fma_f32 v22, -v22, v25, v24
	v_div_fmas_f32 v22, v22, v23, v25
	v_div_fixup_f32 v19, v22, v19, v33
	v_div_scale_f32 v22, s[2:3], v18, v18, v32
	v_rcp_f32_e32 v23, v22
	s_nop 0
	v_fma_f32 v24, -v22, v23, 1.0
	v_fmac_f32_e32 v23, v24, v23
	v_div_scale_f32 v24, vcc, v32, v18, v32
	v_mul_f32_e32 v25, v24, v23
	v_fma_f32 v26, -v22, v25, v24
	v_fmac_f32_e32 v25, v26, v23
	v_fma_f32 v22, -v22, v25, v24
	v_div_fmas_f32 v22, v22, v23, v25
	v_div_fixup_f32 v18, v22, v18, v32
	v_pk_mul_f32 v[76:77], v[20:21], v[18:19]
	v_cmp_nlt_f32_e32 vcc, s34, v34
	v_pk_fma_f32 v[16:17], v[76:77], v[76:77], v[16:17]
	v_mul_f32_e32 v18, v77, v77
	v_pk_add_f32 v[16:17], v[18:19], v[16:17] op_sel_hi:[0,1]
	v_mul_f32_e32 v18, 0xbfb8aa3b, v34
	v_fma_f32 v19, v34, s43, -v18
	v_rndne_f32_e32 v20, v18
	v_fmac_f32_e32 v19, 0xb2a5705f, v34
	v_sub_f32_e32 v18, v18, v20
	v_add_f32_e32 v18, v18, v19
	v_exp_f32_e32 v18, v18
	v_cvt_i32_f32_e32 v19, v20
	v_ldexp_f32 v18, v18, v19
	v_mul_f32_e32 v19, 0xbfb8aa3b, v35
	v_fma_f32 v20, v35, s43, -v19
	v_rndne_f32_e32 v21, v19
	v_fmac_f32_e32 v20, 0xb2a5705f, v35
	v_sub_f32_e32 v19, v19, v21
	v_add_f32_e32 v19, v19, v20
	v_exp_f32_e32 v19, v19
	v_cvt_i32_f32_e32 v20, v21
	v_cndmask_b32_e32 v18, 0, v18, vcc
	v_cmp_ngt_f32_e32 vcc, s35, v34
	v_ldexp_f32 v19, v19, v20
	s_nop 0
	v_cndmask_b32_e32 v18, v179, v18, vcc
	v_cmp_nlt_f32_e32 vcc, s34, v35
	v_pk_fma_f32 v[20:21], v[30:31], v[126:127], v[38:39] op_sel_hi:[1,0,1]
	s_nop 0
	v_cndmask_b32_e32 v19, 0, v19, vcc
	v_cmp_ngt_f32_e32 vcc, s35, v35
	s_nop 1
	v_cndmask_b32_e32 v19, v179, v19, vcc
	v_pk_add_f32 v[18:19], v[18:19], 1.0 op_sel_hi:[1,0]
	s_nop 0
	v_div_scale_f32 v22, s[2:3], v19, v19, v35
	v_rcp_f32_e32 v23, v22
	s_nop 0
	v_fma_f32 v24, -v22, v23, 1.0
	v_fmac_f32_e32 v23, v24, v23
	v_div_scale_f32 v24, vcc, v35, v19, v35
	v_mul_f32_e32 v25, v24, v23
	v_fma_f32 v26, -v22, v25, v24
	v_fmac_f32_e32 v25, v26, v23
	v_fma_f32 v22, -v22, v25, v24
	v_div_fmas_f32 v22, v22, v23, v25
	v_div_fixup_f32 v19, v22, v19, v35
	v_div_scale_f32 v22, s[2:3], v18, v18, v34
	v_rcp_f32_e32 v23, v22
	s_nop 0
	v_fma_f32 v24, -v22, v23, 1.0
	v_fmac_f32_e32 v23, v24, v23
	v_div_scale_f32 v24, vcc, v34, v18, v34
	v_mul_f32_e32 v25, v24, v23
	v_fma_f32 v26, -v22, v25, v24
	v_fmac_f32_e32 v25, v26, v23
	v_fma_f32 v22, -v22, v25, v24
	v_div_fmas_f32 v22, v22, v23, v25
	v_div_fixup_f32 v18, v22, v18, v34
	v_pk_mul_f32 v[124:125], v[20:21], v[18:19]
	s_nop 0
	v_pk_fma_f32 v[16:17], v[124:125], v[124:125], v[16:17]
	v_mul_f32_e32 v18, v125, v125
	v_pk_add_f32 v[128:129], v[18:19], v[16:17] op_sel_hi:[0,1]
	s_waitcnt vmcnt(7)
	v_pk_fma_f32 v[0:1], v[0:1], v[126:127], v[186:187] op_sel_hi:[1,0,1]
	s_waitcnt vmcnt(6)
	v_mul_f32_e32 v103, 0xbfb8aa3b, v190
	v_fma_f32 v105, v190, s43, -v103
	v_rndne_f32_e32 v107, v103
	v_fmac_f32_e32 v105, 0xb2a5705f, v190
	v_sub_f32_e32 v103, v103, v107
	v_add_f32_e32 v103, v103, v105
	v_exp_f32_e32 v103, v103
	v_cvt_i32_f32_e32 v105, v107
	v_cmp_nlt_f32_e32 vcc, s34, v190
	v_ldexp_f32 v103, v103, v105
	s_nop 0
	v_cndmask_b32_e32 v103, 0, v103, vcc
	v_cmp_ngt_f32_e32 vcc, s35, v190
	s_nop 1
	v_cndmask_b32_e32 v130, v179, v103, vcc
	v_mul_f32_e32 v103, 0xbfb8aa3b, v191
	v_fma_f32 v105, v191, s43, -v103
	v_rndne_f32_e32 v107, v103
	v_fmac_f32_e32 v105, 0xb2a5705f, v191
	v_sub_f32_e32 v103, v103, v107
	v_add_f32_e32 v103, v103, v105
	v_exp_f32_e32 v103, v103
	v_cvt_i32_f32_e32 v105, v107
	v_cmp_nlt_f32_e32 vcc, s34, v191
	v_ldexp_f32 v103, v103, v105
	s_nop 0
	v_cndmask_b32_e32 v103, 0, v103, vcc
	v_cmp_ngt_f32_e32 vcc, s35, v191
	s_nop 1
	v_cndmask_b32_e32 v131, v179, v103, vcc
	v_pk_add_f32 v[36:37], v[130:131], 1.0 op_sel_hi:[1,0]
	s_nop 0
	v_div_scale_f32 v103, s[2:3], v37, v37, v191
	v_rcp_f32_e32 v105, v103
	s_nop 0
	v_fma_f32 v107, -v103, v105, 1.0
	v_fmac_f32_e32 v105, v107, v105
	v_div_scale_f32 v107, vcc, v191, v37, v191
	v_mul_f32_e32 v109, v107, v105
	v_fma_f32 v127, -v103, v109, v107
	v_fmac_f32_e32 v109, v127, v105
	v_fma_f32 v103, -v103, v109, v107
	v_div_fmas_f32 v103, v103, v105, v109
	v_div_fixup_f32 v33, v103, v37, v191
	v_div_scale_f32 v37, s[2:3], v36, v36, v190
	v_rcp_f32_e32 v103, v37
	v_pk_fma_f32 v[2:3], v[2:3], v[126:127], v[188:189] op_sel_hi:[1,0,1]
	s_waitcnt vmcnt(5)
	v_pk_fma_f32 v[4:5], v[4:5], v[126:127], v[194:195] op_sel_hi:[1,0,1]
	v_pk_fma_f32 v[6:7], v[6:7], v[126:127], v[196:197] op_sel_hi:[1,0,1]
	v_fma_f32 v105, -v37, v103, 1.0
	v_fmac_f32_e32 v103, v105, v103
	v_div_scale_f32 v105, vcc, v190, v36, v190
	v_mul_f32_e32 v107, v105, v103
	v_fma_f32 v109, -v37, v107, v105
	v_fmac_f32_e32 v107, v109, v103
	v_fma_f32 v37, -v37, v107, v105
	v_div_fmas_f32 v37, v37, v103, v107
	v_div_fixup_f32 v32, v37, v36, v190
	v_pk_mul_f32 v[0:1], v[0:1], v[32:33]
	v_cmp_nlt_f32_e32 vcc, s34, v192
	v_pk_fma_f32 v[32:33], v[0:1], v[0:1], v[128:129]
	v_mul_f32_e32 v36, v1, v1
	v_pk_add_f32 v[32:33], v[36:37], v[32:33] op_sel_hi:[0,1]
	v_mul_f32_e32 v36, 0xbfb8aa3b, v192
	v_fma_f32 v37, v192, s43, -v36
	v_rndne_f32_e32 v103, v36
	v_fmac_f32_e32 v37, 0xb2a5705f, v192
	v_sub_f32_e32 v36, v36, v103
	v_add_f32_e32 v36, v36, v37
	v_exp_f32_e32 v36, v36
	v_cvt_i32_f32_e32 v37, v103
	s_waitcnt vmcnt(3)
	v_pk_fma_f32 v[8:9], v[8:9], v[126:127], v[202:203] op_sel_hi:[1,0,1]
	v_pk_fma_f32 v[10:11], v[10:11], v[126:127], v[204:205] op_sel_hi:[1,0,1]
	s_waitcnt vmcnt(1)
	v_pk_fma_f32 v[12:13], v[12:13], v[126:127], v[210:211] op_sel_hi:[1,0,1]
	v_ldexp_f32 v36, v36, v37
	v_mul_f32_e32 v37, 0xbfb8aa3b, v193
	v_fma_f32 v103, v193, s43, -v37
	v_rndne_f32_e32 v105, v37
	v_fmac_f32_e32 v103, 0xb2a5705f, v193
	v_sub_f32_e32 v37, v37, v105
	v_add_f32_e32 v37, v37, v103
	v_exp_f32_e32 v37, v37
	v_cvt_i32_f32_e32 v103, v105
	v_cndmask_b32_e32 v36, 0, v36, vcc
	v_cmp_ngt_f32_e32 vcc, s35, v192
	v_pk_fma_f32 v[14:15], v[14:15], v[126:127], v[212:213] op_sel_hi:[1,0,1]
	v_ldexp_f32 v37, v37, v103
	v_cndmask_b32_e32 v36, v179, v36, vcc
	v_cmp_nlt_f32_e32 vcc, s34, v193
	s_nop 1
	v_cndmask_b32_e32 v37, 0, v37, vcc
	v_cmp_ngt_f32_e32 vcc, s35, v193
	s_nop 1
	v_cndmask_b32_e32 v37, v179, v37, vcc
	v_pk_add_f32 v[36:37], v[36:37], 1.0 op_sel_hi:[1,0]
	s_nop 0
	v_div_scale_f32 v38, s[2:3], v37, v37, v193
	v_rcp_f32_e32 v39, v38
	s_nop 0
	v_fma_f32 v103, -v38, v39, 1.0
	v_fmac_f32_e32 v39, v103, v39
	v_div_scale_f32 v103, vcc, v193, v37, v193
	v_mul_f32_e32 v105, v103, v39
	v_fma_f32 v107, -v38, v105, v103
	v_fmac_f32_e32 v105, v107, v39
	v_fma_f32 v38, -v38, v105, v103
	v_div_fmas_f32 v38, v38, v39, v105
	v_div_fixup_f32 v35, v38, v37, v193
	v_div_scale_f32 v37, s[2:3], v36, v36, v192
	v_rcp_f32_e32 v38, v37
	s_nop 0
	v_fma_f32 v39, -v37, v38, 1.0
	v_fmac_f32_e32 v38, v39, v38
	v_div_scale_f32 v39, vcc, v192, v36, v192
	v_mul_f32_e32 v103, v39, v38
	v_fma_f32 v105, -v37, v103, v39
	v_fmac_f32_e32 v103, v105, v38
	v_fma_f32 v37, -v37, v103, v39
	v_div_fmas_f32 v37, v37, v38, v103
	v_div_fixup_f32 v34, v37, v36, v192
	v_pk_mul_f32 v[2:3], v[2:3], v[34:35]
	v_cmp_nlt_f32_e32 vcc, s34, v198
	v_pk_fma_f32 v[32:33], v[2:3], v[2:3], v[32:33]
	v_mul_f32_e32 v34, v3, v3
	v_pk_add_f32 v[32:33], v[34:35], v[32:33] op_sel_hi:[0,1]
	v_mul_f32_e32 v34, 0xbfb8aa3b, v198
	v_fma_f32 v35, v198, s43, -v34
	v_rndne_f32_e32 v36, v34
	v_fmac_f32_e32 v35, 0xb2a5705f, v198
	v_sub_f32_e32 v34, v34, v36
	v_add_f32_e32 v34, v34, v35
	v_exp_f32_e32 v34, v34
	v_cvt_i32_f32_e32 v35, v36
	v_ldexp_f32 v34, v34, v35
	v_mul_f32_e32 v35, 0xbfb8aa3b, v199
	v_fma_f32 v36, v199, s43, -v35
	v_rndne_f32_e32 v37, v35
	v_fmac_f32_e32 v36, 0xb2a5705f, v199
	v_sub_f32_e32 v35, v35, v37
	v_add_f32_e32 v35, v35, v36
	v_exp_f32_e32 v35, v35
	v_cvt_i32_f32_e32 v36, v37
	v_cndmask_b32_e32 v34, 0, v34, vcc
	v_cmp_ngt_f32_e32 vcc, s35, v198
	v_ldexp_f32 v35, v35, v36
	s_nop 0
	v_cndmask_b32_e32 v34, v179, v34, vcc
	v_cmp_nlt_f32_e32 vcc, s34, v199
	s_nop 1
	v_cndmask_b32_e32 v35, 0, v35, vcc
	v_cmp_ngt_f32_e32 vcc, s35, v199
	s_nop 1
	v_cndmask_b32_e32 v35, v179, v35, vcc
	v_pk_add_f32 v[28:29], v[34:35], 1.0 op_sel_hi:[1,0]
	s_nop 0
	v_div_scale_f32 v34, s[2:3], v29, v29, v199
	v_rcp_f32_e32 v35, v34
	s_nop 0
	v_fma_f32 v36, -v34, v35, 1.0
	v_fmac_f32_e32 v35, v36, v35
	v_div_scale_f32 v36, vcc, v199, v29, v199
	v_mul_f32_e32 v37, v36, v35
	v_fma_f32 v38, -v34, v37, v36
	v_fmac_f32_e32 v37, v38, v35
	v_fma_f32 v34, -v34, v37, v36
	v_div_fmas_f32 v34, v34, v35, v37
	v_div_fixup_f32 v25, v34, v29, v199
	v_div_scale_f32 v29, s[2:3], v28, v28, v198
	v_rcp_f32_e32 v34, v29
	s_nop 0
	v_fma_f32 v35, -v29, v34, 1.0
	v_fmac_f32_e32 v34, v35, v34
	v_div_scale_f32 v35, vcc, v198, v28, v198
	v_mul_f32_e32 v36, v35, v34
	v_fma_f32 v37, -v29, v36, v35
	v_fmac_f32_e32 v36, v37, v34
	v_fma_f32 v29, -v29, v36, v35
	v_div_fmas_f32 v29, v29, v34, v36
	v_div_fixup_f32 v24, v29, v28, v198
	v_pk_mul_f32 v[4:5], v[4:5], v[24:25]
	v_cmp_nlt_f32_e32 vcc, s34, v200
	v_pk_fma_f32 v[24:25], v[4:5], v[4:5], v[32:33]
	v_mul_f32_e32 v28, v5, v5
	v_pk_add_f32 v[24:25], v[28:29], v[24:25] op_sel_hi:[0,1]
	v_mul_f32_e32 v28, 0xbfb8aa3b, v200
	v_fma_f32 v29, v200, s43, -v28
	v_rndne_f32_e32 v32, v28
	v_fmac_f32_e32 v29, 0xb2a5705f, v200
	v_sub_f32_e32 v28, v28, v32
	v_add_f32_e32 v28, v28, v29
	v_exp_f32_e32 v28, v28
	v_cvt_i32_f32_e32 v29, v32
	v_ldexp_f32 v28, v28, v29
	v_mul_f32_e32 v29, 0xbfb8aa3b, v201
	v_fma_f32 v32, v201, s43, -v29
	v_rndne_f32_e32 v33, v29
	v_fmac_f32_e32 v32, 0xb2a5705f, v201
	v_sub_f32_e32 v29, v29, v33
	v_add_f32_e32 v29, v29, v32
	v_exp_f32_e32 v29, v29
	v_cvt_i32_f32_e32 v32, v33
	v_cndmask_b32_e32 v28, 0, v28, vcc
	v_cmp_ngt_f32_e32 vcc, s35, v200
	v_ldexp_f32 v29, v29, v32
	s_nop 0
	v_cndmask_b32_e32 v28, v179, v28, vcc
	v_cmp_nlt_f32_e32 vcc, s34, v201
	s_nop 1
	v_cndmask_b32_e32 v29, 0, v29, vcc
	v_cmp_ngt_f32_e32 vcc, s35, v201
	s_nop 1
	v_cndmask_b32_e32 v29, v179, v29, vcc
	v_pk_add_f32 v[28:29], v[28:29], 1.0 op_sel_hi:[1,0]
	s_nop 0
	v_div_scale_f32 v30, s[2:3], v29, v29, v201
	v_rcp_f32_e32 v31, v30
	s_nop 0
	v_fma_f32 v32, -v30, v31, 1.0
	v_fmac_f32_e32 v31, v32, v31
	v_div_scale_f32 v32, vcc, v201, v29, v201
	v_mul_f32_e32 v33, v32, v31
	v_fma_f32 v34, -v30, v33, v32
	v_fmac_f32_e32 v33, v34, v31
	v_fma_f32 v30, -v30, v33, v32
	v_div_fmas_f32 v30, v30, v31, v33
	v_div_fixup_f32 v27, v30, v29, v201
	v_div_scale_f32 v29, s[2:3], v28, v28, v200
	v_rcp_f32_e32 v30, v29
	s_nop 0
	v_fma_f32 v31, -v29, v30, 1.0
	v_fmac_f32_e32 v30, v31, v30
	v_div_scale_f32 v31, vcc, v200, v28, v200
	v_mul_f32_e32 v32, v31, v30
	v_fma_f32 v33, -v29, v32, v31
	v_fmac_f32_e32 v32, v33, v30
	v_fma_f32 v29, -v29, v32, v31
	v_div_fmas_f32 v29, v29, v30, v32
	v_div_fixup_f32 v26, v29, v28, v200
	v_pk_mul_f32 v[6:7], v[6:7], v[26:27]
	v_cmp_nlt_f32_e32 vcc, s34, v206
	v_pk_fma_f32 v[24:25], v[6:7], v[6:7], v[24:25]
	v_mul_f32_e32 v26, v7, v7
	v_pk_add_f32 v[24:25], v[26:27], v[24:25] op_sel_hi:[0,1]
	v_mul_f32_e32 v26, 0xbfb8aa3b, v206
	v_fma_f32 v27, v206, s43, -v26
	v_rndne_f32_e32 v28, v26
	v_fmac_f32_e32 v27, 0xb2a5705f, v206
	v_sub_f32_e32 v26, v26, v28
	v_add_f32_e32 v26, v26, v27
	v_exp_f32_e32 v26, v26
	v_cvt_i32_f32_e32 v27, v28
	v_ldexp_f32 v26, v26, v27
	v_mul_f32_e32 v27, 0xbfb8aa3b, v207
	v_fma_f32 v28, v207, s43, -v27
	v_rndne_f32_e32 v29, v27
	v_fmac_f32_e32 v28, 0xb2a5705f, v207
	v_sub_f32_e32 v27, v27, v29
	v_add_f32_e32 v27, v27, v28
	v_exp_f32_e32 v27, v27
	v_cvt_i32_f32_e32 v28, v29
	v_cndmask_b32_e32 v26, 0, v26, vcc
	v_cmp_ngt_f32_e32 vcc, s35, v206
	v_ldexp_f32 v27, v27, v28
	s_nop 0
	v_cndmask_b32_e32 v26, v179, v26, vcc
	v_cmp_nlt_f32_e32 vcc, s34, v207
	s_nop 1
	v_cndmask_b32_e32 v27, 0, v27, vcc
	v_cmp_ngt_f32_e32 vcc, s35, v207
	s_nop 1
	v_cndmask_b32_e32 v27, v179, v27, vcc
	v_pk_add_f32 v[20:21], v[26:27], 1.0 op_sel_hi:[1,0]
	s_nop 0
	v_div_scale_f32 v26, s[2:3], v21, v21, v207
	v_rcp_f32_e32 v27, v26
	s_nop 0
	v_fma_f32 v28, -v26, v27, 1.0
	v_fmac_f32_e32 v27, v28, v27
	v_div_scale_f32 v28, vcc, v207, v21, v207
	v_mul_f32_e32 v29, v28, v27
	v_fma_f32 v30, -v26, v29, v28
	v_fmac_f32_e32 v29, v30, v27
	v_fma_f32 v26, -v26, v29, v28
	v_div_fmas_f32 v26, v26, v27, v29
	v_div_fixup_f32 v17, v26, v21, v207
	v_div_scale_f32 v21, s[2:3], v20, v20, v206
	v_rcp_f32_e32 v26, v21
	s_nop 0
	v_fma_f32 v27, -v21, v26, 1.0
	v_fmac_f32_e32 v26, v27, v26
	v_div_scale_f32 v27, vcc, v206, v20, v206
	v_mul_f32_e32 v28, v27, v26
	v_fma_f32 v29, -v21, v28, v27
	v_fmac_f32_e32 v28, v29, v26
	v_fma_f32 v21, -v21, v28, v27
	v_div_fmas_f32 v21, v21, v26, v28
	v_div_fixup_f32 v16, v21, v20, v206
	v_pk_mul_f32 v[8:9], v[8:9], v[16:17]
	v_cmp_nlt_f32_e32 vcc, s34, v208
	v_pk_fma_f32 v[16:17], v[8:9], v[8:9], v[24:25]
	v_mul_f32_e32 v20, v9, v9
	v_pk_add_f32 v[16:17], v[20:21], v[16:17] op_sel_hi:[0,1]
	v_mul_f32_e32 v20, 0xbfb8aa3b, v208
	v_fma_f32 v21, v208, s43, -v20
	v_rndne_f32_e32 v24, v20
	v_fmac_f32_e32 v21, 0xb2a5705f, v208
	v_sub_f32_e32 v20, v20, v24
	v_add_f32_e32 v20, v20, v21
	v_exp_f32_e32 v20, v20
	v_cvt_i32_f32_e32 v21, v24
	v_ldexp_f32 v20, v20, v21
	v_mul_f32_e32 v21, 0xbfb8aa3b, v209
	v_fma_f32 v24, v209, s43, -v21
	v_rndne_f32_e32 v25, v21
	v_fmac_f32_e32 v24, 0xb2a5705f, v209
	v_sub_f32_e32 v21, v21, v25
	v_add_f32_e32 v21, v21, v24
	v_exp_f32_e32 v21, v21
	v_cvt_i32_f32_e32 v24, v25
	v_cndmask_b32_e32 v20, 0, v20, vcc
	v_cmp_ngt_f32_e32 vcc, s35, v208
	v_ldexp_f32 v21, v21, v24
	s_nop 0
	v_cndmask_b32_e32 v20, v179, v20, vcc
	v_cmp_nlt_f32_e32 vcc, s34, v209
	s_nop 1
	v_cndmask_b32_e32 v21, 0, v21, vcc
	v_cmp_ngt_f32_e32 vcc, s35, v209
	s_nop 1
	v_cndmask_b32_e32 v21, v179, v21, vcc
	v_pk_add_f32 v[20:21], v[20:21], 1.0 op_sel_hi:[1,0]
	s_nop 0
	v_div_scale_f32 v22, s[2:3], v21, v21, v209
	v_rcp_f32_e32 v23, v22
	s_nop 0
	v_fma_f32 v24, -v22, v23, 1.0
	v_fmac_f32_e32 v23, v24, v23
	v_div_scale_f32 v24, vcc, v209, v21, v209
	v_mul_f32_e32 v25, v24, v23
	v_fma_f32 v26, -v22, v25, v24
	v_fmac_f32_e32 v25, v26, v23
	v_fma_f32 v22, -v22, v25, v24
	v_div_fmas_f32 v22, v22, v23, v25
	v_div_fixup_f32 v19, v22, v21, v209
	v_div_scale_f32 v21, s[2:3], v20, v20, v208
	v_rcp_f32_e32 v22, v21
	s_nop 0
	v_fma_f32 v23, -v21, v22, 1.0
	v_fmac_f32_e32 v22, v23, v22
	v_div_scale_f32 v23, vcc, v208, v20, v208
	v_mul_f32_e32 v24, v23, v22
	v_fma_f32 v25, -v21, v24, v23
	v_fmac_f32_e32 v24, v25, v22
	v_fma_f32 v21, -v21, v24, v23
	v_div_fmas_f32 v21, v21, v22, v24
	v_div_fixup_f32 v18, v21, v20, v208
	v_pk_mul_f32 v[10:11], v[10:11], v[18:19]
	s_waitcnt vmcnt(0)
	v_cmp_nlt_f32_e32 vcc, s34, v214
	v_pk_fma_f32 v[16:17], v[10:11], v[10:11], v[16:17]
	v_mul_f32_e32 v18, v11, v11
	v_pk_add_f32 v[16:17], v[18:19], v[16:17] op_sel_hi:[0,1]
	v_mul_f32_e32 v18, 0xbfb8aa3b, v214
	v_fma_f32 v19, v214, s43, -v18
	v_rndne_f32_e32 v20, v18
	v_fmac_f32_e32 v19, 0xb2a5705f, v214
	v_sub_f32_e32 v18, v18, v20
	v_add_f32_e32 v18, v18, v19
	v_exp_f32_e32 v18, v18
	v_cvt_i32_f32_e32 v19, v20
	v_ldexp_f32 v18, v18, v19
	v_mul_f32_e32 v19, 0xbfb8aa3b, v215
	v_fma_f32 v20, v215, s43, -v19
	v_rndne_f32_e32 v21, v19
	v_fmac_f32_e32 v20, 0xb2a5705f, v215
	v_sub_f32_e32 v19, v19, v21
	v_add_f32_e32 v19, v19, v20
	v_exp_f32_e32 v19, v19
	v_cvt_i32_f32_e32 v20, v21
	v_cndmask_b32_e32 v18, 0, v18, vcc
	v_cmp_ngt_f32_e32 vcc, s35, v214
	v_ldexp_f32 v19, v19, v20
	s_nop 0
	v_cndmask_b32_e32 v18, v179, v18, vcc
	v_cmp_nlt_f32_e32 vcc, s34, v215
	s_nop 1
	v_cndmask_b32_e32 v19, 0, v19, vcc
	v_cmp_ngt_f32_e32 vcc, s35, v215
	s_nop 1
	v_cndmask_b32_e32 v19, v179, v19, vcc
	v_pk_add_f32 v[18:19], v[18:19], 1.0 op_sel_hi:[1,0]
	s_nop 0
	v_div_scale_f32 v20, s[2:3], v19, v19, v215
	v_rcp_f32_e32 v21, v20
	s_nop 0
	v_fma_f32 v22, -v20, v21, 1.0
	v_fmac_f32_e32 v21, v22, v21
	v_div_scale_f32 v22, vcc, v215, v19, v215
	v_mul_f32_e32 v23, v22, v21
	v_fma_f32 v24, -v20, v23, v22
	v_fmac_f32_e32 v23, v24, v21
	v_fma_f32 v20, -v20, v23, v22
	v_div_fmas_f32 v20, v20, v21, v23
	v_div_fixup_f32 v19, v20, v19, v215
	v_div_scale_f32 v20, s[2:3], v18, v18, v214
	v_rcp_f32_e32 v21, v20
	s_nop 0
	v_fma_f32 v22, -v20, v21, 1.0
	v_fmac_f32_e32 v21, v22, v21
	v_div_scale_f32 v22, vcc, v214, v18, v214
	v_mul_f32_e32 v23, v22, v21
	v_fma_f32 v24, -v20, v23, v22
	v_fmac_f32_e32 v23, v24, v21
	v_fma_f32 v20, -v20, v23, v22
	v_div_fmas_f32 v20, v20, v21, v23
	v_div_fixup_f32 v18, v20, v18, v214
	v_pk_mul_f32 v[12:13], v[12:13], v[18:19]
	v_cmp_nlt_f32_e32 vcc, s34, v216
	v_pk_fma_f32 v[16:17], v[12:13], v[12:13], v[16:17]
	v_mul_f32_e32 v18, v13, v13
	v_pk_add_f32 v[16:17], v[18:19], v[16:17] op_sel_hi:[0,1]
	v_mul_f32_e32 v18, 0xbfb8aa3b, v216
	v_fma_f32 v19, v216, s43, -v18
	v_rndne_f32_e32 v20, v18
	v_fmac_f32_e32 v19, 0xb2a5705f, v216
	v_sub_f32_e32 v18, v18, v20
	v_add_f32_e32 v18, v18, v19
	v_exp_f32_e32 v18, v18
	v_cvt_i32_f32_e32 v19, v20
	v_ldexp_f32 v18, v18, v19
	v_mul_f32_e32 v19, 0xbfb8aa3b, v217
	v_fma_f32 v20, v217, s43, -v19
	v_rndne_f32_e32 v21, v19
	v_fmac_f32_e32 v20, 0xb2a5705f, v217
	v_sub_f32_e32 v19, v19, v21
	v_add_f32_e32 v19, v19, v20
	v_exp_f32_e32 v19, v19
	v_cvt_i32_f32_e32 v20, v21
	v_cndmask_b32_e32 v18, 0, v18, vcc
	v_cmp_ngt_f32_e32 vcc, s35, v216
	v_ldexp_f32 v19, v19, v20
	s_nop 0
	v_cndmask_b32_e32 v18, v179, v18, vcc
	v_cmp_nlt_f32_e32 vcc, s34, v217
	s_nop 1
	v_cndmask_b32_e32 v19, 0, v19, vcc
	v_cmp_ngt_f32_e32 vcc, s35, v217
	s_nop 1
	v_cndmask_b32_e32 v19, v179, v19, vcc
	v_pk_add_f32 v[18:19], v[18:19], 1.0 op_sel_hi:[1,0]
	s_nop 0
	v_div_scale_f32 v20, s[2:3], v19, v19, v217
	v_rcp_f32_e32 v21, v20
	s_nop 0
	v_fma_f32 v22, -v20, v21, 1.0
	v_fmac_f32_e32 v21, v22, v21
	v_div_scale_f32 v22, vcc, v217, v19, v217
	v_mul_f32_e32 v23, v22, v21
	v_fma_f32 v24, -v20, v23, v22
	v_fmac_f32_e32 v23, v24, v21
	v_fma_f32 v20, -v20, v23, v22
	v_div_fmas_f32 v20, v20, v21, v23
	v_div_fixup_f32 v19, v20, v19, v217
	v_div_scale_f32 v20, s[2:3], v18, v18, v216
	v_rcp_f32_e32 v21, v20
	s_nop 0
	v_fma_f32 v22, -v20, v21, 1.0
	v_fmac_f32_e32 v21, v22, v21
	v_div_scale_f32 v22, vcc, v216, v18, v216
	v_mul_f32_e32 v23, v22, v21
	v_fma_f32 v24, -v20, v23, v22
	v_fmac_f32_e32 v23, v24, v21
	v_fma_f32 v20, -v20, v23, v22
	v_div_fmas_f32 v20, v20, v21, v23
	v_div_fixup_f32 v18, v20, v18, v216
	v_pk_mul_f32 v[14:15], v[14:15], v[18:19]
	s_nop 0
	v_pk_fma_f32 v[16:17], v[14:15], v[14:15], v[16:17]
	v_mul_f32_e32 v18, v15, v15
	v_pk_add_f32 v[16:17], v[18:19], v[16:17] op_sel_hi:[0,1]
	v_mov_b32_e32 v17, v16
	s_nop 1
	v_permlane32_swap_b32_e32 v16, v17
	s_and_saveexec_b64 s[4:5], s[48:49]
	s_cbranch_execz .LBB0_1284
	v_add_f32_e32 v16, v16, v17
	ds_write_b32 v97, v16 offset:1024
	s_branch .LBB0_1284
